# priority: per-block s_setprio flips around the attention MFMA clusters removed (no s_setprio left in the kernel)
# speedup vs baseline: 1.0037x; 1.0037x over previous
; #define LAS __attribute__((address_space(3)))
; template <bool MASK>
; __device__ __forceinline__ void sb_weights(f32x16& p0, f32x16& p1, float tlf, int hi, float& R) {
;     ...
;             for (int j = 0; j < 4; ++j) {
;                 const float z = hf ? p1[4 * a + j] : p0[4 * a + j];
;                 const float o_ = __builtin_amdgcn_rcpf(1.0f + __builtin_amdgcn_exp2f(z));
;                 if (MASK) { const float vf_ = __builtin_amdgcn_fmed3f(tlf - (float)(32 * hf + 8 * a + j), 0.f, 1.f), dl = o_ - 1.0f; om[j] = __builtin_fmaf(vf_, dl, 1.0f); be[j] = -vf_ * dl; }
;                 else { om[j] = o_; be[j] = 1.0f - o_; }
; template <int VAR>
; __device__ __forceinline__ void attn_unit(LAS unsigned char* lds, const AttnArgs& A, int b, int h, int qb, const int tid) {
;     ...
;                 f32x16 p0, p1;
; #pragma unroll
;                 for (int r = 0; r < 16; ++r) { p0[r] = 0.f; p1[r] = 0.f; }
;                 __builtin_amdgcn_s_setprio(1);
; #pragma unroll
;                 for (int d0 = 0; d0 < 4; ++d0) {
;                     const bf16x8 b0 = *(const LAS bf16x8*)(kb + d0 * 2048), b1 = *(const LAS bf16x8*)(kb + d0 * 2048 + 512);
;                     p0 = __builtin_amdgcn_mfma_f32_32x32x16_bf16(b0, qr[d0], p0, 0, 0, 0);
;                     p1 = __builtin_amdgcn_mfma_f32_32x32x16_bf16(b1, qr[d0], p1, 0, 0, 0);
;                 }
;                 __builtin_amdgcn_s_setprio(0);
.LBB0_435:
	s_add_i32 s38, s85, 2
	s_and_b32 s70, s83, 1
	s_cmp_gt_i32 s38, s13
	s_cselect_b64 s[38:39], -1, 0
	s_or_b64 s[38:39], s[38:39], s[68:69]
	s_and_b64 vcc, exec, s[38:39]
	s_cbranch_vccnz .LBB0_443
	s_lshl_b32 s50, s70, 13
	v_add_u32_e32 v0, s50, v125
	s_cmp_lg_u32 s84, s83
	ds_read_b128 v[224:227], v0
	ds_read_b128 v[228:231], v0 offset:512
	ds_read_b128 v[232:235], v0 offset:2048
	ds_read_b128 v[236:239], v0 offset:2560
	ds_read_b128 v[240:243], v0 offset:4096
	ds_read_b128 v[244:247], v0 offset:4608
	ds_read_b128 v[248:251], v0 offset:6144
	ds_read_b128 v[2:5], v0 offset:6656
	v_add_u32_e32 v194, s50, v177
	s_waitcnt vmcnt(5) lgkmcnt(7)
	v_mfma_f32_32x32x16_bf16 v[64:79], v[224:227], v[80:83], 0
	s_waitcnt lgkmcnt(6)
	v_mfma_f32_32x32x16_bf16 v[48:63], v[228:231], v[80:83], 0
	s_waitcnt vmcnt(4) lgkmcnt(5)
	v_mfma_f32_32x32x16_bf16 v[64:79], v[232:235], v[84:87], v[64:79]
	s_waitcnt lgkmcnt(4)
	v_mfma_f32_32x32x16_bf16 v[48:63], v[236:239], v[84:87], v[48:63]
	s_waitcnt vmcnt(3) lgkmcnt(3)
	v_mfma_f32_32x32x16_bf16 v[64:79], v[240:243], v[88:91], v[64:79]
	s_waitcnt lgkmcnt(2)
	v_mfma_f32_32x32x16_bf16 v[48:63], v[244:247], v[88:91], v[48:63]
	s_waitcnt vmcnt(2) lgkmcnt(1)
	v_mfma_f32_32x32x16_bf16 v[64:79], v[248:251], v[92:95], v[64:79]
	s_waitcnt lgkmcnt(0)
	v_mfma_f32_32x32x16_bf16 v[48:63], v[2:5], v[92:95], v[48:63]
	ds_read_b64_tr_b16 v[224:225], v194 offset:16384
	ds_read_b64_tr_b16 v[226:227], v194 offset:16896
	ds_read_b64_tr_b16 v[228:229], v194 offset:17408
	ds_read_b64_tr_b16 v[230:231], v194 offset:17920
	ds_read_b64_tr_b16 v[232:233], v194 offset:18432
	ds_read_b64_tr_b16 v[234:235], v194 offset:18944
	ds_read_b64_tr_b16 v[236:237], v194 offset:19456
	ds_read_b64_tr_b16 v[238:239], v194 offset:19968
	ds_read_b64_tr_b16 v[240:241], v194 offset:20480
	ds_read_b64_tr_b16 v[242:243], v194 offset:20992
	ds_read_b64_tr_b16 v[244:245], v194 offset:21504
	ds_read_b64_tr_b16 v[246:247], v194 offset:22016
	ds_read_b64_tr_b16 v[248:249], v194 offset:22528
	ds_read_b64_tr_b16 v[250:251], v194 offset:23040
	s_nop 7
	v_exp_f32_e32 v0, v64
	v_exp_f32_e32 v221, v65
	v_exp_f32_e32 v219, v66
	v_exp_f32_e32 v218, v67
	v_add_f32_e32 v0, 1.0, v0
	v_rcp_f32_e32 v64, v0
	v_exp_f32_e32 v220, v68
	v_exp_f32_e32 v217, v69
	v_exp_f32_e32 v216, v70
	v_exp_f32_e32 v215, v71
	v_exp_f32_e32 v214, v72
	v_exp_f32_e32 v213, v73
	v_exp_f32_e32 v212, v74
	v_exp_f32_e32 v210, v75
	v_exp_f32_e32 v211, v76
	v_exp_f32_e32 v209, v77
	v_exp_f32_e32 v208, v78
	v_exp_f32_e32 v207, v79
	v_exp_f32_e32 v206, v48
	v_exp_f32_e32 v205, v49
	v_exp_f32_e32 v193, v50
	v_exp_f32_e32 v191, v51
	v_exp_f32_e32 v192, v52
	v_exp_f32_e32 v190, v53
	v_exp_f32_e32 v189, v54
	v_exp_f32_e32 v188, v55
	v_exp_f32_e32 v187, v56
	v_exp_f32_e32 v186, v57
	v_exp_f32_e32 v185, v58
	v_exp_f32_e32 v183, v59
	v_exp_f32_e32 v184, v60
	v_exp_f32_e32 v182, v61
	v_exp_f32_e32 v181, v62
	v_exp_f32_e32 v180, v63
	s_mov_b64 s[68:69], -1
	s_cbranch_scc0 .LBB0_438
; template <bool MASK>
; __device__ __forceinline__ void sb_weights(f32x16& p0, f32x16& p1, float tlf, int hi, float& R) {
;     ...
;             for (int j = 0; j < 4; ++j) {
;                 const float z = hf ? p1[4 * a + j] : p0[4 * a + j];
;                 const float o_ = __builtin_amdgcn_rcpf(1.0f + __builtin_amdgcn_exp2f(z));
;                 if (MASK) { const float vf_ = __builtin_amdgcn_fmed3f(tlf - (float)(32 * hf + 8 * a + j), 0.f, 1.f), dl = o_ - 1.0f; om[j] = __builtin_fmaf(vf_, dl, 1.0f); be[j] = -vf_ * dl; }
;                 else { om[j] = o_; be[j] = 1.0f - o_; }
;             }
;             const float s2 = om[3], s1 = om[3] * om[2], s0 = s1 * om[1];
;             Tm[4 * hf + a] = s0 * om[0];
;             if (hf) { p1[4 * a + 3] = be[3]; p1[4 * a + 2] = be[2] * s2; p1[4 * a + 1] = be[1] * s1; p1[4 * a] = be[0] * s0; }
;             else    { p0[4 * a + 3] = be[3]; p0[4 * a + 2] = be[2] * s2; p0[4 * a + 1] = be[1] * s1; p0[4 * a] = be[0] * s0; }
;         }
;     float U[8], Th[8], PS[8];
; #pragma unroll
;     for (int k = 0; k < 8; ++k) { float lo_; lohi(Tm[k], lo_, Th[k]); U[k] = lo_ * Th[k]; }
	v_add_f32_e32 v7, 1.0, v217
	v_add_f32_e32 v0, 1.0, v221
	v_rcp_f32_e32 v10, v7
	v_add_f32_e32 v7, 1.0, v216
	v_rcp_f32_e32 v65, v0
	v_add_f32_e32 v0, 1.0, v219
	v_rcp_f32_e32 v11, v7
	v_add_f32_e32 v7, 1.0, v215
	v_rcp_f32_e32 v4, v0
	v_add_f32_e32 v0, 1.0, v218
	v_rcp_f32_e32 v7, v7
	v_rcp_f32_e32 v6, v0
	v_add_f32_e32 v5, 1.0, v220
	v_rcp_f32_e32 v5, v5
	v_mul_f32_e32 v14, v7, v11
	v_mul_f32_e32 v9, v6, v4
	v_mul_f32_e32 v49, v10, v14
	v_pk_add_f32 v[2:3], v[64:65], 1.0 op_sel_hi:[1,0] neg_lo:[1,0] neg_hi:[1,0]
	v_mul_f32_e32 v8, v65, v9
	v_pk_add_f32 v[12:13], v[4:5], 1.0 op_sel_hi:[1,0] neg_lo:[1,0] neg_hi:[1,0]
	v_mul_f32_e32 v68, v5, v49
	v_pk_add_f32 v[4:5], v[6:7], 1.0 op_sel_hi:[1,0] neg_lo:[1,0] neg_hi:[1,0]
	v_mov_b32_e32 v15, v7
	v_add_f32_e32 v7, 1.0, v214
	v_mul_f32_e32 v0, v64, v8
	v_pk_mul_f32 v[2:3], v[2:3], v[8:9]
	v_pk_add_f32 v[8:9], v[10:11], 1.0 op_sel_hi:[1,0] neg_lo:[1,0] neg_hi:[1,0]
	v_rcp_f32_e32 v10, v7
	v_add_f32_e32 v7, 1.0, v213
	v_rcp_f32_e32 v11, v7
	v_add_f32_e32 v7, 1.0, v212
	v_pk_mul_f32 v[8:9], v[14:15], v[8:9]
	v_rcp_f32_e32 v14, v7
	v_add_f32_e32 v7, 1.0, v210
	v_rcp_f32_e32 v48, v7
	v_mov_b32_e32 v7, v49
	v_pk_mul_f32 v[6:7], v[6:7], v[12:13]
	v_pk_add_f32 v[12:13], v[10:11], 1.0 op_sel_hi:[1,0] neg_lo:[1,0] neg_hi:[1,0]
	v_mul_f32_e32 v51, v48, v14
	v_mul_f32_e32 v50, v11, v51
	v_mul_f32_e32 v69, v10, v50
	v_add_f32_e32 v10, 1.0, v211
	v_rcp_f32_e32 v15, v10
	v_add_f32_e32 v10, 1.0, v209
	v_rcp_f32_e32 v52, v10
	v_add_f32_e32 v10, 1.0, v208
	v_rcp_f32_e32 v53, v10
	v_add_f32_e32 v10, 1.0, v207
	v_rcp_f32_e32 v49, v10
	v_pk_mul_f32 v[10:11], v[12:13], v[50:51]
	v_pk_add_f32 v[50:51], v[14:15], 1.0 op_sel_hi:[1,0] neg_lo:[1,0] neg_hi:[1,0]
	v_pk_add_f32 v[12:13], v[52:53], 1.0 op_sel_hi:[1,0] neg_lo:[1,0] neg_hi:[1,0]
	v_mul_f32_e32 v54, v49, v53
	v_mul_f32_e32 v57, v52, v54
	v_mul_f32_e32 v75, v15, v57
	v_pk_add_f32 v[14:15], v[48:49], 1.0 op_sel_hi:[1,0] neg_lo:[1,0] neg_hi:[1,0]
	v_mov_b32_e32 v55, v49
	v_add_f32_e32 v49, 1.0, v206
	v_rcp_f32_e32 v52, v49
	v_add_f32_e32 v49, 1.0, v205
	v_rcp_f32_e32 v53, v49
	v_add_f32_e32 v49, 1.0, v193
	v_pk_mul_f32 v[12:13], v[54:55], v[12:13]
	v_rcp_f32_e32 v54, v49
	v_add_f32_e32 v49, 1.0, v191
	v_rcp_f32_e32 v56, v49
	v_mov_b32_e32 v49, v57
	v_pk_mul_f32 v[48:49], v[48:49], v[50:51]
	v_pk_add_f32 v[50:51], v[52:53], 1.0 op_sel_hi:[1,0] neg_lo:[1,0] neg_hi:[1,0]
	v_mul_f32_e32 v59, v56, v54
	v_mul_f32_e32 v58, v53, v59
	v_mul_f32_e32 v74, v52, v58
	v_add_f32_e32 v52, 1.0, v192
	v_add_f32_e32 v53, 1.0, v189
	v_add_f32_e32 v57, 1.0, v188
	v_rcp_f32_e32 v55, v52
	v_add_f32_e32 v52, 1.0, v190
	v_rcp_f32_e32 v53, v53
	v_rcp_f32_e32 v57, v57
	v_rcp_f32_e32 v52, v52
	v_pk_mul_f32 v[50:51], v[50:51], v[58:59]
	v_pk_add_f32 v[58:59], v[54:55], 1.0 op_sel_hi:[1,0] neg_lo:[1,0] neg_hi:[1,0]
	v_mul_f32_e32 v62, v57, v53
	v_mul_f32_e32 v65, v52, v62
	v_pk_add_f32 v[60:61], v[52:53], 1.0 op_sel_hi:[1,0] neg_lo:[1,0] neg_hi:[1,0]
	v_mul_f32_e32 v79, v55, v65
	v_pk_add_f32 v[54:55], v[56:57], 1.0 op_sel_hi:[1,0] neg_lo:[1,0] neg_hi:[1,0]
	v_mov_b32_e32 v63, v57
	v_add_f32_e32 v57, 1.0, v187
	v_pk_mul_f32 v[52:53], v[62:63], v[60:61]
	v_rcp_f32_e32 v60, v57
	v_add_f32_e32 v57, 1.0, v186
	v_rcp_f32_e32 v61, v57
	v_add_f32_e32 v57, 1.0, v185
	v_rcp_f32_e32 v62, v57
	v_add_f32_e32 v57, 1.0, v183
	v_rcp_f32_e32 v66, v57
	v_mov_b32_e32 v57, v65
	v_pk_mul_f32 v[56:57], v[56:57], v[58:59]
	v_pk_add_f32 v[58:59], v[60:61], 1.0 op_sel_hi:[1,0] neg_lo:[1,0] neg_hi:[1,0]
	v_mul_f32_e32 v71, v66, v62
	v_mul_f32_e32 v70, v61, v71
	v_mul_f32_e32 v78, v60, v70
	v_add_f32_e32 v60, 1.0, v184
	v_rcp_f32_e32 v63, v60
	v_add_f32_e32 v60, 1.0, v182
	v_add_f32_e32 v61, 1.0, v181
	v_add_f32_e32 v65, 1.0, v180
	v_rcp_f32_e32 v60, v60
	v_rcp_f32_e32 v61, v61
	v_rcp_f32_e32 v67, v65
	v_pk_mul_f32 v[58:59], v[58:59], v[70:71]
	v_pk_add_f32 v[70:71], v[62:63], 1.0 op_sel_hi:[1,0] neg_lo:[1,0] neg_hi:[1,0]
	v_pk_add_f32 v[72:73], v[60:61], 1.0 op_sel_hi:[1,0] neg_lo:[1,0] neg_hi:[1,0]
	v_mul_f32_e32 v76, v67, v61
	v_mov_b32_e32 v77, v67
	v_mul_f32_e32 v65, v60, v76
	v_pk_mul_f32 v[60:61], v[76:77], v[72:73]
	v_mov_b32_e32 v73, v75
	v_mov_b32_e32 v72, v74
	v_mul_f32_e32 v222, v63, v65
	v_pk_add_f32 v[62:63], v[66:67], 1.0 op_sel_hi:[1,0] neg_lo:[1,0] neg_hi:[1,0]
	v_mov_b32_e32 v67, v65
	v_permlane32_swap_b32_e32 v75, v73
	v_permlane32_swap_b32_e32 v74, v72
	v_pk_mul_f32 v[66:67], v[66:67], v[70:71]
	v_mov_b32_e32 v70, v68
	v_mov_b32_e32 v71, v69
	v_pk_mul_f32 v[76:77], v[74:75], v[72:73]
	v_mov_b32_e32 v75, v79
	v_mov_b32_e32 v74, v78
	v_mov_b32_e32 v65, v0
	v_permlane32_swap_b32_e32 v68, v70
	v_permlane32_swap_b32_e32 v69, v71
	v_permlane32_swap_b32_e32 v79, v75
	v_permlane32_swap_b32_e32 v78, v74
	v_mov_b32_e32 v223, v222
	v_permlane32_swap_b32_e32 v0, v65
	v_pk_mul_f32 v[68:69], v[68:69], v[70:71]
	v_pk_mul_f32 v[78:79], v[78:79], v[74:75]
	v_permlane32_swap_b32_e32 v222, v223
	s_mov_b64 s[68:69], 0

; #define LAS __attribute__((address_space(3)))
; __device__ __forceinline__ unsigned cvtpk(float lo, float hi) { f32x2_t v = {lo, hi}; bf16x2_t b = __builtin_convertvector(v, bf16x2_t); return __builtin_bit_cast(unsigned, b); }
; __device__ __forceinline__ s16x4 vtr(const LAS unsigned char* p) { return __builtin_bit_cast(s16x4, __builtin_amdgcn_ds_read_tr16_b64_v4i16((LAS v4i16_t*)p)); }
; __device__ __forceinline__ void pv(f32x16 (&o)[2], const LAS unsigned char* vp, const f32x16& p0, const f32x16& p1) {
;     u32x4 pw[4];
;     pw[0] = (u32x4){cvtpk(p0[0], p0[1]), cvtpk(p0[2], p0[3]), cvtpk(p0[4], p0[5]), cvtpk(p0[6], p0[7])};
;     pw[1] = (u32x4){cvtpk(p0[8], p0[9]), cvtpk(p0[10], p0[11]), cvtpk(p0[12], p0[13]), cvtpk(p0[14], p0[15])};
;     pw[2] = (u32x4){cvtpk(p1[0], p1[1]), cvtpk(p1[2], p1[3]), cvtpk(p1[4], p1[5]), cvtpk(p1[6], p1[7])};
;     pw[3] = (u32x4){cvtpk(p1[8], p1[9]), cvtpk(p1[10], p1[11]), cvtpk(p1[12], p1[13]), cvtpk(p1[14], p1[15])};
;     __builtin_amdgcn_s_setprio(1);
; #pragma unroll
;     for (int dh = 0; dh < 2; ++dh)
; #pragma unroll
;         for (int ks = 0; ks < 4; ++ks) {
;             const s16x4 lo = vtr(vp + dh * 4096 + ks * 1024), hi_ = vtr(vp + dh * 4096 + ks * 1024 + 512);
;             const bf16x8 vf = __builtin_shufflevector(lo, hi_, 0, 1, 2, 3, 4, 5, 6, 7);
;             o[dh] = __builtin_amdgcn_mfma_f32_32x32x16_bf16(__builtin_bit_cast(bf16x8, pw[ks]), vf, o[dh], 0, 0, 0);
;         }
;     __builtin_amdgcn_s_setprio(0);
; template <bool MASK>
; __device__ __forceinline__ void sb_weights(f32x16& p0, f32x16& p1, float tlf, int hi, float& R) {
;     ...
;     PS[7] = 1.0f;
; #pragma unroll
;     for (int k = 6; k >= 0; --k) PS[k] = PS[k + 1] * U[k + 1];
; #pragma unroll
;     for (int k = 0; k < 8; ++k) {
;         const float Bk = PS[k] * (hi ? 1.0f : Th[k]) * R;
; #pragma unroll
;         for (int j = 0; j < 4; ++j) { if (k < 4) p0[4 * k + j] *= Bk; else p1[4 * (k - 4) + j] *= Bk; }
;     }
;     R *= PS[0] * U[0];
.LBB0_440:
	v_mul_f32_e32 v180, v222, v223
	v_mul_f32_e32 v181, v78, v180
	v_mul_f32_e32 v182, v79, v181
	v_mul_f32_e32 v183, v76, v182
	v_mul_f32_e32 v78, v77, v183
	v_mul_f32_e32 v64, v69, v78
	v_cndmask_b32_e64 v69, 1.0, v70, s[8:9]
	v_mul_f32_e32 v69, v64, v69
	v_pk_mov_b32 v[76:77], v[6:7], v[8:9] op_sel:[1,0]
	v_mov_b32_e32 v8, v9
	v_mov_b32_e32 v9, v5
	v_cndmask_b32_e64 v5, 1.0, v71, s[8:9]
	v_mul_f32_e32 v70, v179, v69
	v_mul_f32_e32 v5, v78, v5
	v_pk_mul_f32 v[76:77], v[76:77], v[70:71] op_sel_hi:[1,0]
	v_pk_mul_f32 v[8:9], v[8:9], v[70:71] op_sel_hi:[1,0]
	v_mul_f32_e32 v70, v179, v5
	v_cndmask_b32_e64 v5, 1.0, v73, s[8:9]
	v_mov_b32_e32 v78, v48
	v_mov_b32_e32 v79, v14
	v_mul_f32_e32 v5, v183, v5
	v_pk_mul_f32 v[10:11], v[10:11], v[70:71] op_sel_hi:[1,0]
	v_pk_mul_f32 v[70:71], v[78:79], v[70:71] op_sel_hi:[1,0]
	v_mul_f32_e32 v78, v179, v5
	v_cndmask_b32_e64 v5, 1.0, v72, s[8:9]
	v_mov_b32_e32 v14, v13
	v_mul_f32_e32 v5, v182, v5
	v_pk_mov_b32 v[48:49], v[48:49], v[12:13] op_sel:[1,0]
	v_pk_mul_f32 v[12:13], v[14:15], v[78:79] op_sel_hi:[1,0]
	v_mul_f32_e32 v14, v179, v5
	v_cndmask_b32_e64 v5, 1.0, v75, s[8:9]
	v_mov_b32_e32 v72, v56
	v_mov_b32_e32 v73, v54
	v_mul_f32_e32 v5, v181, v5
	v_pk_mul_f32 v[50:51], v[50:51], v[14:15] op_sel_hi:[1,0]
	v_pk_mul_f32 v[14:15], v[72:73], v[14:15] op_sel_hi:[1,0]
	v_mul_f32_e32 v72, v179, v5
	v_cndmask_b32_e64 v5, 1.0, v74, s[8:9]
	v_pk_mov_b32 v[56:57], v[56:57], v[52:53] op_sel:[1,0]
	v_mov_b32_e32 v54, v53
	v_mul_f32_e32 v5, v180, v5
	v_pk_mul_f32 v[56:57], v[56:57], v[72:73] op_sel_hi:[1,0]
	v_pk_mul_f32 v[52:53], v[54:55], v[72:73] op_sel_hi:[1,0]
	v_mul_f32_e32 v54, v179, v5
	v_mov_b32_e32 v72, v66
	v_mov_b32_e32 v73, v62
	v_cndmask_b32_e64 v5, 1.0, v223, s[8:9]
	v_pk_mul_f32 v[58:59], v[58:59], v[54:55] op_sel_hi:[1,0]
	v_pk_mul_f32 v[54:55], v[72:73], v[54:55] op_sel_hi:[1,0]
	v_mul_f32_e32 v72, v179, v5
	v_mov_b32_e32 v62, v61
	v_mov_b32_e32 v69, v0
	v_cndmask_b32_e64 v184, 1.0, v65, s[8:9]
	v_pk_mov_b32 v[66:67], v[66:67], v[60:61] op_sel:[1,0]
	v_pk_mul_f32 v[60:61], v[72:73], v[62:63] op_sel_hi:[0,1]
	v_pk_mul_f32 v[62:63], v[68:69], v[64:65]
	v_mov_b32_e32 v7, v4
	v_mul_f32_e32 v0, v62, v184
	v_mul_f32_e32 v0, v179, v0
	v_pk_mul_f32 v[2:3], v[2:3], v[0:1] op_sel_hi:[1,0]
	v_pk_mul_f32 v[4:5], v[6:7], v[0:1] op_sel_hi:[1,0]
	v_mul_f32_e32 v0, v62, v63
	v_pk_mul_f32 v[48:49], v[48:49], v[78:79] op_sel_hi:[1,0]
	v_pk_mul_f32 v[66:67], v[72:73], v[66:67] op_sel_hi:[0,1]
	v_mul_f32_e32 v179, v179, v0
	v_cvt_pk_bf16_f32 v2, v2, v3
	v_cvt_pk_bf16_f32 v3, v4, v5
	v_cvt_pk_bf16_f32 v4, v76, v77
	v_cvt_pk_bf16_f32 v5, v8, v9
	v_cvt_pk_bf16_f32 v6, v10, v11
	v_cvt_pk_bf16_f32 v7, v70, v71
	v_cvt_pk_bf16_f32 v8, v48, v49
	v_cvt_pk_bf16_f32 v9, v12, v13
	v_cvt_pk_bf16_f32 v10, v50, v51
	v_cvt_pk_bf16_f32 v11, v14, v15
	v_cvt_pk_bf16_f32 v12, v56, v57
	v_cvt_pk_bf16_f32 v13, v52, v53
	v_cvt_pk_bf16_f32 v48, v58, v59
	v_cvt_pk_bf16_f32 v49, v54, v55
	v_cvt_pk_bf16_f32 v50, v66, v67
	v_cvt_pk_bf16_f32 v51, v60, v61
	v_add_u32_e32 v0, s50, v177
	ds_read_b64_tr_b16 v[52:53], v0 offset:23552
	ds_read_b64_tr_b16 v[54:55], v0 offset:24064
	s_waitcnt lgkmcnt(2)
	v_mfma_f32_32x32x16_bf16 v[16:31], v[2:5], v[224:227], v[16:31]
	v_mfma_f32_32x32x16_bf16 v[16:31], v[6:9], v[228:231], v[16:31]
	v_mfma_f32_32x32x16_bf16 v[16:31], v[10:13], v[232:235], v[16:31]
	v_mfma_f32_32x32x16_bf16 v[16:31], v[48:51], v[236:239], v[16:31]
	v_mfma_f32_32x32x16_bf16 v[32:47], v[2:5], v[240:243], v[32:47]
	v_mfma_f32_32x32x16_bf16 v[32:47], v[6:9], v[244:247], v[32:47]
	v_mfma_f32_32x32x16_bf16 v[32:47], v[10:13], v[248:251], v[32:47]
	s_waitcnt lgkmcnt(0)
	v_mfma_f32_32x32x16_bf16 v[32:47], v[48:51], v[52:55], v[32:47]
	v_cmp_eq_f32_e32 vcc, 0, v179
	s_cmp_eq_u64 vcc, exec
	s_cselect_b64 s[68:69], -1, 0
	s_add_i32 s50, s83, 1
	s_cmp_ge_u32 s50, s81
	s_cbranch_scc0 .LBB0_444

; #define LAS __attribute__((address_space(3)))
; __device__ __forceinline__ float pair_max(float v) { float a, b; lohi(v, a, b); return fmaxf(a, b); }
; __device__ __forceinline__ void softmax_pv(f32x16& p0, f32x16& p1, float& m, float& l, f32x16 (&o)[2], LAS float* wsf, const LAS unsigned char* vp, int r32, int hi) {
;     float rm = fmaxf(p0[0], p1[0]);
; #pragma unroll
;     for (int r = 1; r < 16; ++r) rm = fmaxf(rm, fmaxf(p0[r], p1[r]));
;     rm = pair_max(rm);
;     if (__all(rm - m < -151.0f)) return;
;     const float mnew = fmaxf(m, rm), alpha = __builtin_amdgcn_exp2f(m - mnew);
;     m = mnew;
;     float s = 0.f;
; #pragma unroll
;     for (int r = 0; r < 16; ++r) { p0[r] = __builtin_amdgcn_exp2f(p0[r] - mnew); p1[r] = __builtin_amdgcn_exp2f(p1[r] - mnew); s += p0[r] + p1[r]; }
;     l = l * alpha + s;
;     if (__any(alpha != 1.0f)) {
;         if (hi == 0) wsf[r32] = alpha;
; #pragma unroll
;         for (int r = 0; r < 16; ++r) { const float f = wsf[(r & 3) + 8 * (r >> 2) + 4 * hi]; o[0][r] *= f; o[1][r] *= f; }
; template <int VAR>
; __device__ __forceinline__ void attn_unit(LAS unsigned char* lds, const AttnArgs& A, int b, int h, int qb, const int tid) {
;     ...
;                 for (int mp = 0; mp < 2; ++mp) {
;                     f32x16 p0, p1;
; #pragma unroll
;                     for (int r = 0; r < 16; ++r) { p0[r] = 0.f; p1[r] = 0.f; }
;                     __builtin_amdgcn_s_setprio(1);
; #pragma unroll
;                     for (int dd = 0; dd < 2; ++dd) {
;                         const int d0 = 2 * mp + dd;
;                         const bf16x8 b0 = *(const LAS bf16x8*)(kb + d0 * 2048), b1 = *(const LAS bf16x8*)(kb + d0 * 2048 + 512);
;                         p0 = __builtin_amdgcn_mfma_f32_32x32x16_bf16(b0, qr[d0], p0, 0, 0, 0);
;                         p1 = __builtin_amdgcn_mfma_f32_32x32x16_bf16(b1, qr[d0], p1, 0, 0, 0);
;                     }
;                     __builtin_amdgcn_s_setprio(0);
; #pragma unroll
;                     for (int r = 0; r < 16; ++r) {
;                         const float c0 = (float)((r & 3) + 8 * (r >> 2));
;                         p0[r] = __builtin_fmaf(-slope2, __builtin_fabsf(tb - c0), p0[r]);
;                         p1[r] = __builtin_fmaf(-slope2, __builtin_fabsf(tb - (c0 + 32.0f)), p1[r]);
;                     }
.LBB0_453:
	s_add_i32 s38, s84, 2
	s_and_b32 s71, s70, 1
	s_cmp_gt_i32 s38, s81
	s_cselect_b64 s[38:39], -1, 0
	s_or_b64 s[38:39], s[38:39], s[12:13]
	s_and_b64 vcc, exec, s[38:39]
	s_cbranch_vccnz .LBB0_460
	v_add_u32_e32 v66, v140, v141
	v_cvt_f32_i32_e32 v134, v66
	s_lshl_b32 s50, s71, 13
	v_add_u32_e32 v145, s50, v136
	ds_read_b128 v[66:69], v145
	ds_read_b128 v[82:85], v145 offset:512
	ds_read_b128 v[146:149], v145 offset:2048
	s_waitcnt lgkmcnt(2)
	v_mfma_f32_32x32x16_bf16 v[66:81], v[66:69], v[98:101], 0
	s_waitcnt lgkmcnt(0)
	v_mfma_f32_32x32x16_bf16 v[66:81], v[146:149], v[102:105], v[66:81]
	ds_read_b128 v[146:149], v145 offset:2560
	v_mfma_f32_32x32x16_bf16 v[82:97], v[82:85], v[98:101], 0
	s_waitcnt lgkmcnt(0)
	v_mfma_f32_32x32x16_bf16 v[82:97], v[146:149], v[102:105], v[82:97]
	v_add_u32_e32 v253, s50, v137
	ds_read_b64_tr_b16 v[222:223], v253 offset:16384
	ds_read_b64_tr_b16 v[224:225], v253 offset:16896
	ds_read_b64_tr_b16 v[226:227], v253 offset:17408
	ds_read_b64_tr_b16 v[228:229], v253 offset:17920
	ds_read_b64_tr_b16 v[230:231], v253 offset:18432
	ds_read_b64_tr_b16 v[232:233], v253 offset:18944
	ds_read_b64_tr_b16 v[234:235], v253 offset:19456
	ds_read_b64_tr_b16 v[236:237], v253 offset:19968
	ds_read_b64_tr_b16 v[238:239], v253 offset:20480
	ds_read_b64_tr_b16 v[240:241], v253 offset:20992
	ds_read_b64_tr_b16 v[242:243], v253 offset:21504
	ds_read_b64_tr_b16 v[244:245], v253 offset:22016
	ds_read_b64_tr_b16 v[246:247], v253 offset:22528
	ds_read_b64_tr_b16 v[248:249], v253 offset:23040
	ds_read_b64_tr_b16 v[250:251], v253 offset:23552
	ds_read_b64_tr_b16 v[252:253], v253 offset:24064
	v_add_f32_e32 v147, -1.0, v134
	v_add_f32_e32 v148, 0xc2040000, v134
	v_add_f32_e32 v146, 0xc2000000, v134
	s_nop 3
	v_fma_f32 v213, v138, |v147|, v67
	s_nop 2
	v_fma_f32 v214, v138, |v148|, v83
	v_add_f32_e32 v149, -2.0, v134
	v_add_f32_e32 v150, 0xc2080000, v134
	v_add_f32_e32 v151, 0xc0400000, v134
	v_add_f32_e32 v152, 0xc20c0000, v134
	v_add_f32_e32 v173, 0xc1800000, v134
	v_add_f32_e32 v182, 0xc1980000, v134
	v_fma_f32 v215, v138, |v134|, v66
	v_fma_f32 v216, v138, |v146|, v82
	v_fma_f32 v211, v138, |v149|, v68
	v_fma_f32 v212, v138, |v150|, v84
	v_fma_f32 v209, v138, |v151|, v69
	v_fma_f32 v210, v138, |v152|, v85
	v_add_f32_e32 v153, 0xc1000000, v134
	v_add_f32_e32 v166, 0xc2200000, v134
	v_add_f32_e32 v167, 0xc1100000, v134
	v_add_f32_e32 v168, 0xc2240000, v134
	v_add_f32_e32 v169, 0xc1200000, v134
	v_fma_f32 v85, v138, |v173|, v74
	v_fma_f32 v74, v138, |v182|, v77
	v_add_f32_e32 v184, 0xc1c00000, v134
	v_add_f32_e32 v186, 0xc1c80000, v134
	v_max_f32_e32 v77, v213, v214
	v_fma_f32 v207, v138, |v153|, v70
	v_fma_f32 v208, v138, |v166|, v86
	v_fma_f32 v205, v138, |v167|, v71
	v_fma_f32 v206, v138, |v168|, v87
	v_fma_f32 v192, v138, |v169|, v72
	v_add_f32_e32 v170, 0xc2280000, v134
	v_add_f32_e32 v171, 0xc1300000, v134
	v_add_f32_e32 v172, 0xc22c0000, v134
	v_fma_f32 v72, v138, |v184|, v78
	v_fma_f32 v70, v138, |v186|, v79
	v_max3_f32 v77, v215, v216, v77
	v_max_f32_e32 v78, v211, v212
	v_max_f32_e32 v79, v209, v210
	v_fma_f32 v193, v138, |v170|, v88
	v_fma_f32 v87, v138, |v171|, v73
	v_fma_f32 v88, v138, |v172|, v89
	v_add_f32_e32 v177, 0xc2400000, v134
	v_add_f32_e32 v178, 0xc1880000, v134
	v_add_f32_e32 v179, 0xc2440000, v134
	v_max3_f32 v77, v77, v78, v79
	v_max_f32_e32 v78, v207, v208
	v_max_f32_e32 v79, v205, v206
	v_fma_f32 v86, v138, |v177|, v90
	v_fma_f32 v83, v138, |v178|, v75
	v_fma_f32 v84, v138, |v179|, v91
	v_add_f32_e32 v180, 0xc1900000, v134
	v_add_f32_e32 v181, 0xc2480000, v134
	v_add_f32_e32 v183, 0xc24c0000, v134
	v_max3_f32 v77, v77, v78, v79
	v_max_f32_e32 v78, v192, v193
	v_max_f32_e32 v79, v87, v88
	v_fma_f32 v76, v138, |v180|, v76
	v_fma_f32 v82, v138, |v181|, v92
	v_fma_f32 v75, v138, |v183|, v93
	v_add_f32_e32 v185, 0xc2600000, v134
	v_add_f32_e32 v187, 0xc2640000, v134
	v_max3_f32 v77, v77, v78, v79
	v_max_f32_e32 v78, v85, v86
	v_max_f32_e32 v79, v83, v84
	v_fma_f32 v73, v138, |v185|, v94
	v_fma_f32 v71, v138, |v187|, v95
	v_add_f32_e32 v188, 0xc1d00000, v134
	v_add_f32_e32 v189, 0xc2680000, v134
	v_add_f32_e32 v190, 0xc1d80000, v134
	v_add_f32_e32 v191, 0xc26c0000, v134
	v_max3_f32 v77, v77, v78, v79
	v_max_f32_e32 v78, v76, v82
	v_max_f32_e32 v79, v74, v75
	v_fma_f32 v68, v138, |v188|, v80
	v_fma_f32 v69, v138, |v189|, v96
	v_fma_f32 v66, v138, |v190|, v81
	v_fma_f32 v67, v138, |v191|, v97
	v_max3_f32 v77, v77, v78, v79
	v_max_f32_e32 v78, v72, v73
	v_max_f32_e32 v79, v70, v71
	v_max3_f32 v77, v77, v78, v79
	v_max_f32_e32 v78, v68, v69
	v_max_f32_e32 v79, v66, v67
	v_max3_f32 v77, v77, v78, v79
	v_mov_b32_e32 v78, v77
	s_nop 1
	v_permlane32_swap_b32_e32 v77, v78
	v_max_f32_e32 v78, v78, v78
	v_max_f32_e32 v77, v77, v77
	v_max_f32_e32 v77, v77, v78
	v_sub_f32_e32 v78, v77, v217
	v_cmp_gt_f32_e32 vcc, s36, v78
	s_cmp_eq_u64 vcc, exec
	s_cbranch_scc1 .LBB0_461
	v_max_f32_e32 v77, v77, v77
	v_add_f32_e32 v78, 0x41000000, v217
	v_cmp_gt_f32_e32 vcc, v77, v78
	s_nop 1
	v_cndmask_b32_e32 v135, v217, v77, vcc
	v_sub_f32_e32 v77, v217, v135
	v_exp_f32_e32 v77, v77
	s_nop 0
	v_cmp_neq_f32_e32 vcc, 1.0, v77
	s_cbranch_vccz .LBB0_459
	s_and_saveexec_b64 s[12:13], s[8:9]
	ds_write_b32 v139, v77 offset:36864
	s_or_b64 exec, exec, s[12:13]
	v_add_u32_e32 v89, s69, v0
	ds_read_b128 v[78:81], v89 offset:36960
	ds_read_b128 v[90:93], v89 offset:36928
	ds_read_b128 v[94:97], v89 offset:36896
	ds_read_b128 v[218:221], v89 offset:36864
	s_waitcnt lgkmcnt(3)
	v_pk_mul_f32 v[62:63], v[62:63], v[78:79]
	s_waitcnt lgkmcnt(2)
	v_pk_mul_f32 v[58:59], v[58:59], v[90:91]
	s_waitcnt lgkmcnt(1)
	v_pk_mul_f32 v[54:55], v[54:55], v[94:95]
	v_pk_mul_f32 v[64:65], v[64:65], v[80:81]
	v_pk_mul_f32 v[60:61], v[60:61], v[92:93]
	v_pk_mul_f32 v[56:57], v[56:57], v[96:97]
	s_waitcnt lgkmcnt(0)
	v_pk_mul_f32 v[52:53], v[52:53], v[220:221]
	v_pk_mul_f32 v[50:51], v[50:51], v[218:219]
	v_pk_mul_f32 v[46:47], v[46:47], v[78:79]
	v_pk_mul_f32 v[42:43], v[42:43], v[90:91]
	v_pk_mul_f32 v[38:39], v[38:39], v[94:95]
	v_pk_mul_f32 v[48:49], v[48:49], v[80:81]
	v_pk_mul_f32 v[44:45], v[44:45], v[92:93]
	v_pk_mul_f32 v[40:41], v[40:41], v[96:97]
	v_pk_mul_f32 v[36:37], v[36:37], v[220:221]
	v_pk_mul_f32 v[34:35], v[34:35], v[218:219]
; #define LAS __attribute__((address_space(3)))
; __device__ __forceinline__ unsigned cvtpk(float lo, float hi) { f32x2_t v = {lo, hi}; bf16x2_t b = __builtin_convertvector(v, bf16x2_t); return __builtin_bit_cast(unsigned, b); }
; __device__ __forceinline__ s16x4 vtr(const LAS unsigned char* p) { return __builtin_bit_cast(s16x4, __builtin_amdgcn_ds_read_tr16_b64_v4i16((LAS v4i16_t*)p)); }
; __device__ __forceinline__ void pv(f32x16 (&o)[2], const LAS unsigned char* vp, const f32x16& p0, const f32x16& p1) {
;     u32x4 pw[4];
;     pw[0] = (u32x4){cvtpk(p0[0], p0[1]), cvtpk(p0[2], p0[3]), cvtpk(p0[4], p0[5]), cvtpk(p0[6], p0[7])};
;     pw[1] = (u32x4){cvtpk(p0[8], p0[9]), cvtpk(p0[10], p0[11]), cvtpk(p0[12], p0[13]), cvtpk(p0[14], p0[15])};
;     pw[2] = (u32x4){cvtpk(p1[0], p1[1]), cvtpk(p1[2], p1[3]), cvtpk(p1[4], p1[5]), cvtpk(p1[6], p1[7])};
;     pw[3] = (u32x4){cvtpk(p1[8], p1[9]), cvtpk(p1[10], p1[11]), cvtpk(p1[12], p1[13]), cvtpk(p1[14], p1[15])};
;     __builtin_amdgcn_s_setprio(1);
; #pragma unroll
;     for (int dh = 0; dh < 2; ++dh)
; #pragma unroll
;         for (int ks = 0; ks < 4; ++ks) {
;             const s16x4 lo = vtr(vp + dh * 4096 + ks * 1024), hi_ = vtr(vp + dh * 4096 + ks * 1024 + 512);
;             const bf16x8 vf = __builtin_shufflevector(lo, hi_, 0, 1, 2, 3, 4, 5, 6, 7);
;             o[dh] = __builtin_amdgcn_mfma_f32_32x32x16_bf16(__builtin_bit_cast(bf16x8, pw[ks]), vf, o[dh], 0, 0, 0);
;         }
;     __builtin_amdgcn_s_setprio(0);
; __device__ __forceinline__ void softmax_pv(f32x16& p0, f32x16& p1, float& m, float& l, f32x16 (&o)[2], LAS float* wsf, const LAS unsigned char* vp, int r32, int hi) {
;     ...
;     const float mnew = fmaxf(m, rm), alpha = __builtin_amdgcn_exp2f(m - mnew);
;     m = mnew;
;     float s = 0.f;
; #pragma unroll
;     for (int r = 0; r < 16; ++r) { p0[r] = __builtin_amdgcn_exp2f(p0[r] - mnew); p1[r] = __builtin_amdgcn_exp2f(p1[r] - mnew); s += p0[r] + p1[r]; }
;     l = l * alpha + s;
;     if (__any(alpha != 1.0f)) {
;         if (hi == 0) wsf[r32] = alpha;
; #pragma unroll
;         for (int r = 0; r < 16; ++r) { const float f = wsf[(r & 3) + 8 * (r >> 2) + 4 * hi]; o[0][r] *= f; o[1][r] *= f; }
;     }
;     pv(o, vp, p0, p1);
.LBB0_459:
	v_sub_f32_e32 v78, v215, v135
	v_sub_f32_e32 v79, v216, v135
	v_exp_f32_e32 v78, v78
	v_exp_f32_e32 v79, v79
	v_sub_f32_e32 v80, v213, v135
	v_sub_f32_e32 v81, v214, v135
	v_exp_f32_e32 v80, v80
	v_exp_f32_e32 v81, v81
	v_sub_f32_e32 v91, v211, v135
	v_sub_f32_e32 v92, v212, v135
	v_exp_f32_e32 v91, v91
	v_exp_f32_e32 v92, v92
	v_sub_f32_e32 v93, v209, v135
	v_sub_f32_e32 v94, v210, v135
	v_exp_f32_e32 v93, v93
	v_exp_f32_e32 v94, v94
	v_sub_f32_e32 v95, v207, v135
	v_sub_f32_e32 v96, v208, v135
	v_add_f32_e32 v89, v78, v79
	v_exp_f32_e32 v95, v95
	v_exp_f32_e32 v96, v96
	v_sub_f32_e32 v97, v205, v135
	v_sub_f32_e32 v194, v206, v135
	v_add_f32_e32 v89, 0, v89
	v_add_f32_e32 v90, v80, v81
	v_exp_f32_e32 v97, v97
	v_exp_f32_e32 v194, v194
	v_sub_f32_e32 v192, v192, v135
	v_sub_f32_e32 v193, v193, v135
	v_add_f32_e32 v89, v90, v89
	v_add_f32_e32 v90, v91, v92
	v_exp_f32_e32 v192, v192
	v_exp_f32_e32 v193, v193
	v_sub_f32_e32 v87, v87, v135
	v_sub_f32_e32 v88, v88, v135
	v_add_f32_e32 v89, v90, v89
	v_add_f32_e32 v90, v93, v94
	v_exp_f32_e32 v87, v87
	v_exp_f32_e32 v88, v88
	v_sub_f32_e32 v85, v85, v135
	v_sub_f32_e32 v86, v86, v135
	v_add_f32_e32 v89, v90, v89
	v_add_f32_e32 v90, v95, v96
	v_exp_f32_e32 v85, v85
	v_exp_f32_e32 v86, v86
	v_sub_f32_e32 v83, v83, v135
	v_sub_f32_e32 v84, v84, v135
	v_add_f32_e32 v89, v90, v89
	v_add_f32_e32 v90, v97, v194
	v_exp_f32_e32 v83, v83
	v_exp_f32_e32 v84, v84
	v_sub_f32_e32 v76, v76, v135
	v_sub_f32_e32 v82, v82, v135
	v_add_f32_e32 v89, v90, v89
	v_add_f32_e32 v90, v192, v193
	v_exp_f32_e32 v76, v76
	v_exp_f32_e32 v82, v82
	v_sub_f32_e32 v74, v74, v135
	v_sub_f32_e32 v75, v75, v135
	v_add_f32_e32 v89, v90, v89
	v_add_f32_e32 v90, v87, v88
	v_exp_f32_e32 v74, v74
	v_exp_f32_e32 v195, v75
	v_add_f32_e32 v89, v90, v89
	v_add_f32_e32 v90, v85, v86
	v_add_f32_e32 v89, v90, v89
	v_add_f32_e32 v90, v83, v84
	v_add_f32_e32 v75, v90, v89
	v_add_f32_e32 v89, v76, v82
	v_sub_f32_e32 v72, v72, v135
	v_sub_f32_e32 v73, v73, v135
	v_sub_f32_e32 v70, v70, v135
	v_add_f32_e32 v75, v89, v75
	v_add_f32_e32 v89, v74, v195
	v_exp_f32_e32 v72, v72
	v_exp_f32_e32 v90, v73
	v_exp_f32_e32 v73, v70
	v_sub_f32_e32 v70, v71, v135
	v_sub_f32_e32 v68, v68, v135
	v_exp_f32_e32 v205, v70
	v_add_f32_e32 v70, v89, v75
	v_exp_f32_e32 v75, v68
	v_sub_f32_e32 v68, v69, v135
	v_sub_f32_e32 v66, v66, v135
	v_exp_f32_e32 v89, v68
	v_exp_f32_e32 v206, v66
	v_sub_f32_e32 v66, v67, v135
	v_exp_f32_e32 v207, v66
	v_add_f32_e32 v71, v72, v90
	v_add_f32_e32 v70, v71, v70
	v_add_f32_e32 v71, v73, v205
	v_add_f32_e32 v66, v71, v70
	v_add_f32_e32 v67, v75, v89
	v_add_f32_e32 v66, v67, v66
	v_add_f32_e32 v67, v206, v207
	v_add_f32_e32 v208, v67, v66
	v_fmac_f32_e32 v208, v143, v77
	v_cvt_pk_bf16_f32 v66, v78, v80
	v_cvt_pk_bf16_f32 v67, v91, v93
	v_cvt_pk_bf16_f32 v68, v95, v97
	v_cvt_pk_bf16_f32 v69, v192, v87
	v_cvt_pk_bf16_f32 v70, v85, v83
	v_cvt_pk_bf16_f32 v71, v76, v74
	v_cvt_pk_bf16_f32 v72, v72, v73
	v_cvt_pk_bf16_f32 v73, v75, v206
	v_cvt_pk_bf16_f32 v74, v79, v81
	v_cvt_pk_bf16_f32 v75, v92, v94
	v_cvt_pk_bf16_f32 v76, v96, v194
	v_cvt_pk_bf16_f32 v77, v193, v88
	v_cvt_pk_bf16_f32 v78, v86, v84
	v_cvt_pk_bf16_f32 v79, v82, v195
	v_cvt_pk_bf16_f32 v80, v90, v205
	v_cvt_pk_bf16_f32 v81, v89, v207
	s_waitcnt lgkmcnt(0)
	v_mfma_f32_32x32x16_bf16 v[50:65], v[66:69], v[222:225], v[50:65]
	v_mfma_f32_32x32x16_bf16 v[50:65], v[70:73], v[226:229], v[50:65]
	v_mfma_f32_32x32x16_bf16 v[50:65], v[74:77], v[230:233], v[50:65]
	v_mfma_f32_32x32x16_bf16 v[50:65], v[78:81], v[234:237], v[50:65]
	v_mfma_f32_32x32x16_bf16 v[34:49], v[66:69], v[238:241], v[34:49]
	v_mfma_f32_32x32x16_bf16 v[34:49], v[70:73], v[242:245], v[34:49]
	v_mfma_f32_32x32x16_bf16 v[34:49], v[74:77], v[246:249], v[34:49]
	v_mfma_f32_32x32x16_bf16 v[34:49], v[78:81], v[250:253], v[34:49]
	v_mov_b32_e32 v143, v208
	s_branch .LBB0_462

; #define LAS __attribute__((address_space(3)))
; __device__ __forceinline__ float pair_max(float v) { float a, b; lohi(v, a, b); return fmaxf(a, b); }
; __device__ __forceinline__ void softmax_pv(f32x16& p0, f32x16& p1, float& m, float& l, f32x16 (&o)[2], LAS float* wsf, const LAS unsigned char* vp, int r32, int hi) {
;     float rm = fmaxf(p0[0], p1[0]);
; #pragma unroll
;     for (int r = 1; r < 16; ++r) rm = fmaxf(rm, fmaxf(p0[r], p1[r]));
;     rm = pair_max(rm);
;     if (__all(rm - m < -151.0f)) return;
;     const float mnew = fmaxf(m, rm), alpha = __builtin_amdgcn_exp2f(m - mnew);
;     m = mnew;
;     float s = 0.f;
; #pragma unroll
;     for (int r = 0; r < 16; ++r) { p0[r] = __builtin_amdgcn_exp2f(p0[r] - mnew); p1[r] = __builtin_amdgcn_exp2f(p1[r] - mnew); s += p0[r] + p1[r]; }
;     l = l * alpha + s;
;     if (__any(alpha != 1.0f)) {
;         if (hi == 0) wsf[r32] = alpha;
; #pragma unroll
;         for (int r = 0; r < 16; ++r) { const float f = wsf[(r & 3) + 8 * (r >> 2) + 4 * hi]; o[0][r] *= f; o[1][r] *= f; }
; template <int VAR>
; __device__ __forceinline__ void attn_unit(LAS unsigned char* lds, const AttnArgs& A, int b, int h, int qb, const int tid) {
;     ...
;                 for (int mp = 0; mp < 2; ++mp) {
;                     f32x16 p0, p1;
; #pragma unroll
;                     for (int r = 0; r < 16; ++r) { p0[r] = 0.f; p1[r] = 0.f; }
;                     __builtin_amdgcn_s_setprio(1);
; #pragma unroll
;                     for (int dd = 0; dd < 2; ++dd) {
;                         const int d0 = 2 * mp + dd;
;                         const bf16x8 b0 = *(const LAS bf16x8*)(kb + d0 * 2048), b1 = *(const LAS bf16x8*)(kb + d0 * 2048 + 512);
;                         p0 = __builtin_amdgcn_mfma_f32_32x32x16_bf16(b0, qr[d0], p0, 0, 0, 0);
;                         p1 = __builtin_amdgcn_mfma_f32_32x32x16_bf16(b1, qr[d0], p1, 0, 0, 0);
;                     }
;                     __builtin_amdgcn_s_setprio(0);
; #pragma unroll
;                     for (int r = 0; r < 16; ++r) {
;                         const float c0 = (float)((r & 3) + 8 * (r >> 2));
;                         p0[r] = __builtin_fmaf(-slope2, __builtin_fabsf(tb - c0), p0[r]);
;                         p1[r] = __builtin_fmaf(-slope2, __builtin_fabsf(tb - (c0 + 32.0f)), p1[r]);
;                     }
.LBB0_462:
	ds_read_b128 v[66:69], v145 offset:4096
	ds_read_b128 v[82:85], v145 offset:4608
	ds_read_b128 v[206:209], v145 offset:6144
	s_waitcnt lgkmcnt(2)
	v_mfma_f32_32x32x16_bf16 v[66:81], v[66:69], v[106:109], 0
	s_waitcnt lgkmcnt(0)
	v_mfma_f32_32x32x16_bf16 v[66:81], v[206:209], v[110:113], v[66:81]
	ds_read_b128 v[206:209], v145 offset:6656
	v_mfma_f32_32x32x16_bf16 v[82:97], v[82:85], v[106:109], 0
	s_waitcnt lgkmcnt(0)
	v_mfma_f32_32x32x16_bf16 v[82:97], v[206:209], v[110:113], v[82:97]
	s_nop 6
	v_fma_f32 v207, v138, |v147|, v67
	s_nop 2
	v_fma_f32 v206, v138, |v148|, v83
	v_fma_f32 v209, v138, |v134|, v66
	v_fma_f32 v208, v138, |v146|, v82
	v_fma_f32 v205, v138, |v149|, v68
	v_fma_f32 v193, v138, |v150|, v84
	v_fma_f32 v192, v138, |v151|, v69
	v_fma_f32 v151, v138, |v152|, v85
	v_fma_f32 v84, v138, |v178|, v75
	v_fma_f32 v75, v138, |v182|, v77
	v_max_f32_e32 v77, v207, v206
	v_fma_f32 v150, v138, |v153|, v70
	v_fma_f32 v149, v138, |v166|, v86
	v_fma_f32 v148, v138, |v167|, v71
	v_fma_f32 v147, v138, |v168|, v87
	v_fma_f32 v145, v138, |v170|, v88
	v_fma_f32 v88, v138, |v171|, v73
	v_fma_f32 v73, v138, |v184|, v78
	v_fma_f32 v71, v138, |v186|, v79
	v_max3_f32 v77, v209, v208, v77
	v_max_f32_e32 v78, v205, v193
	v_max_f32_e32 v79, v192, v151
	v_fma_f32 v146, v138, |v169|, v72
	v_fma_f32 v87, v138, |v172|, v89
	v_max3_f32 v77, v77, v78, v79
	v_max_f32_e32 v78, v150, v149
	v_max_f32_e32 v79, v148, v147
	v_fma_f32 v86, v138, |v173|, v74
	v_fma_f32 v85, v138, |v177|, v90
	v_fma_f32 v83, v138, |v179|, v91
	v_max3_f32 v77, v77, v78, v79
	v_max_f32_e32 v78, v146, v145
	v_max_f32_e32 v79, v88, v87
	v_fma_f32 v82, v138, |v180|, v76
	v_fma_f32 v76, v138, |v181|, v92
	v_fma_f32 v74, v138, |v183|, v93
	v_max3_f32 v77, v77, v78, v79
	v_max_f32_e32 v78, v86, v85
	v_max_f32_e32 v79, v84, v83
	v_fma_f32 v72, v138, |v185|, v94
	v_fma_f32 v70, v138, |v187|, v95
	v_max3_f32 v77, v77, v78, v79
	v_max_f32_e32 v78, v82, v76
	v_max_f32_e32 v79, v75, v74
	v_fma_f32 v69, v138, |v188|, v80
	v_fma_f32 v68, v138, |v189|, v96
	v_fma_f32 v67, v138, |v190|, v81
	v_fma_f32 v66, v138, |v191|, v97
	v_max3_f32 v77, v77, v78, v79
	v_max_f32_e32 v78, v73, v72
	v_max_f32_e32 v79, v71, v70
	v_max3_f32 v77, v77, v78, v79
	v_max_f32_e32 v78, v69, v68
	v_max_f32_e32 v79, v67, v66
	v_max3_f32 v77, v77, v78, v79
	v_mov_b32_e32 v78, v77
	s_nop 1
	v_permlane32_swap_b32_e32 v77, v78
	v_max_f32_e32 v78, v78, v78
	v_max_f32_e32 v77, v77, v77
	v_max_f32_e32 v77, v77, v78
	v_sub_f32_e32 v78, v77, v144
	v_cmp_gt_f32_e32 vcc, s36, v78
	s_cmp_eq_u64 vcc, exec
	s_cbranch_scc1 .LBB0_468
	v_max_f32_e32 v77, v77, v77
	v_add_f32_e32 v78, 0x41000000, v144
	v_cmp_gt_f32_e32 vcc, v77, v78
	s_nop 1
	v_cndmask_b32_e32 v134, v144, v77, vcc
	v_sub_f32_e32 v77, v144, v134
	v_exp_f32_e32 v77, v77
	s_nop 0
	v_cmp_neq_f32_e32 vcc, 1.0, v77
	s_cbranch_vccz .LBB0_467
	s_and_saveexec_b64 s[12:13], s[8:9]
	ds_write_b32 v139, v77 offset:36864
	s_or_b64 exec, exec, s[12:13]
	v_add_u32_e32 v89, s69, v0
	ds_read_b128 v[78:81], v89 offset:36960
	ds_read_b128 v[90:93], v89 offset:36928
	ds_read_b128 v[94:97], v89 offset:36896
	ds_read_b128 v[166:169], v89 offset:36864
	s_waitcnt lgkmcnt(3)
	v_pk_mul_f32 v[30:31], v[30:31], v[78:79]
	s_waitcnt lgkmcnt(2)
	v_pk_mul_f32 v[26:27], v[26:27], v[90:91]
	s_waitcnt lgkmcnt(1)
	v_pk_mul_f32 v[22:23], v[22:23], v[94:95]
	v_pk_mul_f32 v[32:33], v[32:33], v[80:81]
	v_pk_mul_f32 v[28:29], v[28:29], v[92:93]
	v_pk_mul_f32 v[24:25], v[24:25], v[96:97]
	s_waitcnt lgkmcnt(0)
	v_pk_mul_f32 v[20:21], v[20:21], v[168:169]
	v_pk_mul_f32 v[18:19], v[18:19], v[166:167]
	v_pk_mul_f32 v[14:15], v[14:15], v[78:79]
	v_pk_mul_f32 v[10:11], v[10:11], v[90:91]
	v_pk_mul_f32 v[6:7], v[6:7], v[94:95]
	v_pk_mul_f32 v[16:17], v[16:17], v[80:81]
	v_pk_mul_f32 v[12:13], v[12:13], v[92:93]
	v_pk_mul_f32 v[8:9], v[8:9], v[96:97]
	v_pk_mul_f32 v[4:5], v[4:5], v[168:169]
	v_pk_mul_f32 v[2:3], v[2:3], v[166:167]
; #define LAS __attribute__((address_space(3)))
; __device__ __forceinline__ unsigned cvtpk(float lo, float hi) { f32x2_t v = {lo, hi}; bf16x2_t b = __builtin_convertvector(v, bf16x2_t); return __builtin_bit_cast(unsigned, b); }
; __device__ __forceinline__ s16x4 vtr(const LAS unsigned char* p) { return __builtin_bit_cast(s16x4, __builtin_amdgcn_ds_read_tr16_b64_v4i16((LAS v4i16_t*)p)); }
; __device__ __forceinline__ void pv(f32x16 (&o)[2], const LAS unsigned char* vp, const f32x16& p0, const f32x16& p1) {
;     u32x4 pw[4];
;     pw[0] = (u32x4){cvtpk(p0[0], p0[1]), cvtpk(p0[2], p0[3]), cvtpk(p0[4], p0[5]), cvtpk(p0[6], p0[7])};
;     pw[1] = (u32x4){cvtpk(p0[8], p0[9]), cvtpk(p0[10], p0[11]), cvtpk(p0[12], p0[13]), cvtpk(p0[14], p0[15])};
;     pw[2] = (u32x4){cvtpk(p1[0], p1[1]), cvtpk(p1[2], p1[3]), cvtpk(p1[4], p1[5]), cvtpk(p1[6], p1[7])};
;     pw[3] = (u32x4){cvtpk(p1[8], p1[9]), cvtpk(p1[10], p1[11]), cvtpk(p1[12], p1[13]), cvtpk(p1[14], p1[15])};
;     __builtin_amdgcn_s_setprio(1);
; #pragma unroll
;     for (int dh = 0; dh < 2; ++dh)
; #pragma unroll
;         for (int ks = 0; ks < 4; ++ks) {
;             const s16x4 lo = vtr(vp + dh * 4096 + ks * 1024), hi_ = vtr(vp + dh * 4096 + ks * 1024 + 512);
;             const bf16x8 vf = __builtin_shufflevector(lo, hi_, 0, 1, 2, 3, 4, 5, 6, 7);
;             o[dh] = __builtin_amdgcn_mfma_f32_32x32x16_bf16(__builtin_bit_cast(bf16x8, pw[ks]), vf, o[dh], 0, 0, 0);
;         }
;     __builtin_amdgcn_s_setprio(0);
; __device__ __forceinline__ void softmax_pv(f32x16& p0, f32x16& p1, float& m, float& l, f32x16 (&o)[2], LAS float* wsf, const LAS unsigned char* vp, int r32, int hi) {
;     ...
;     const float mnew = fmaxf(m, rm), alpha = __builtin_amdgcn_exp2f(m - mnew);
;     m = mnew;
;     float s = 0.f;
; #pragma unroll
;     for (int r = 0; r < 16; ++r) { p0[r] = __builtin_amdgcn_exp2f(p0[r] - mnew); p1[r] = __builtin_amdgcn_exp2f(p1[r] - mnew); s += p0[r] + p1[r]; }
;     l = l * alpha + s;
;     if (__any(alpha != 1.0f)) {
;         if (hi == 0) wsf[r32] = alpha;
; #pragma unroll
;         for (int r = 0; r < 16; ++r) { const float f = wsf[(r & 3) + 8 * (r >> 2) + 4 * hi]; o[0][r] *= f; o[1][r] *= f; }
;     }
;     pv(o, vp, p0, p1);
.LBB0_467:
	v_sub_f32_e32 v78, v209, v134
	v_sub_f32_e32 v79, v208, v134
	v_exp_f32_e32 v78, v78
	v_exp_f32_e32 v79, v79
	v_sub_f32_e32 v80, v207, v134
	v_sub_f32_e32 v81, v206, v134
	v_exp_f32_e32 v80, v80
	v_exp_f32_e32 v81, v81
	v_sub_f32_e32 v91, v205, v134
	v_sub_f32_e32 v92, v193, v134
	v_exp_f32_e32 v91, v91
	v_exp_f32_e32 v92, v92
	v_sub_f32_e32 v93, v192, v134
	v_sub_f32_e32 v94, v151, v134
	v_exp_f32_e32 v93, v93
	v_exp_f32_e32 v94, v94
	v_sub_f32_e32 v95, v150, v134
	v_sub_f32_e32 v96, v149, v134
	v_add_f32_e32 v89, v78, v79
	v_exp_f32_e32 v95, v95
	v_exp_f32_e32 v96, v96
	v_sub_f32_e32 v97, v148, v134
	v_sub_f32_e32 v144, v147, v134
	v_add_f32_e32 v89, 0, v89
	v_add_f32_e32 v90, v80, v81
	v_exp_f32_e32 v97, v97
	v_exp_f32_e32 v144, v144
	v_sub_f32_e32 v146, v146, v134
	v_sub_f32_e32 v145, v145, v134
	v_add_f32_e32 v89, v90, v89
	v_add_f32_e32 v90, v91, v92
	v_exp_f32_e32 v146, v146
	v_exp_f32_e32 v145, v145
	v_sub_f32_e32 v88, v88, v134
	v_sub_f32_e32 v87, v87, v134
	v_add_f32_e32 v89, v90, v89
	v_add_f32_e32 v90, v93, v94
	v_exp_f32_e32 v88, v88
	v_exp_f32_e32 v87, v87
	v_sub_f32_e32 v86, v86, v134
	v_sub_f32_e32 v85, v85, v134
	v_add_f32_e32 v89, v90, v89
	v_add_f32_e32 v90, v95, v96
	v_exp_f32_e32 v86, v86
	v_exp_f32_e32 v85, v85
	v_sub_f32_e32 v84, v84, v134
	v_sub_f32_e32 v83, v83, v134
	v_add_f32_e32 v89, v90, v89
	v_add_f32_e32 v90, v97, v144
	v_exp_f32_e32 v84, v84
	v_exp_f32_e32 v83, v83
	v_sub_f32_e32 v82, v82, v134
	v_sub_f32_e32 v76, v76, v134
	v_add_f32_e32 v89, v90, v89
	v_add_f32_e32 v90, v146, v145
	v_exp_f32_e32 v82, v82
	v_exp_f32_e32 v147, v76
	v_sub_f32_e32 v75, v75, v134
	v_sub_f32_e32 v74, v74, v134
	v_add_f32_e32 v89, v90, v89
	v_add_f32_e32 v90, v88, v87
	v_exp_f32_e32 v75, v75
	v_exp_f32_e32 v148, v74
	v_add_f32_e32 v89, v90, v89
	v_add_f32_e32 v90, v86, v85
	v_add_f32_e32 v89, v90, v89
	v_add_f32_e32 v90, v84, v83
	v_sub_f32_e32 v73, v73, v134
	v_sub_f32_e32 v72, v72, v134
	v_add_f32_e32 v74, v90, v89
	v_add_f32_e32 v76, v82, v147
	v_exp_f32_e32 v73, v73
	v_exp_f32_e32 v89, v72
	v_sub_f32_e32 v71, v71, v134
	v_sub_f32_e32 v70, v70, v134
	v_add_f32_e32 v74, v76, v74
	v_add_f32_e32 v76, v75, v148
	v_exp_f32_e32 v72, v71
	v_exp_f32_e32 v90, v70
	v_sub_f32_e32 v69, v69, v134
	v_sub_f32_e32 v68, v68, v134
	v_add_f32_e32 v70, v76, v74
	v_exp_f32_e32 v74, v69
	v_exp_f32_e32 v149, v68
	v_sub_f32_e32 v67, v67, v134
	v_sub_f32_e32 v66, v66, v134
	v_exp_f32_e32 v76, v67
	v_exp_f32_e32 v150, v66
	v_add_f32_e32 v71, v73, v89
	v_add_f32_e32 v70, v71, v70
	v_add_f32_e32 v71, v72, v90
	v_add_f32_e32 v66, v71, v70
	v_add_f32_e32 v67, v74, v149
	v_add_f32_e32 v66, v67, v66
	v_add_f32_e32 v67, v76, v150
	v_add_f32_e32 v151, v67, v66
	v_fmac_f32_e32 v151, v142, v77
	v_cvt_pk_bf16_f32 v66, v78, v80
	v_cvt_pk_bf16_f32 v67, v91, v93
	v_cvt_pk_bf16_f32 v68, v95, v97
	v_cvt_pk_bf16_f32 v69, v146, v88
	v_cvt_pk_bf16_f32 v70, v86, v84
	v_cvt_pk_bf16_f32 v71, v82, v75
	v_cvt_pk_bf16_f32 v72, v73, v72
	v_cvt_pk_bf16_f32 v73, v74, v76
	v_cvt_pk_bf16_f32 v74, v79, v81
	v_cvt_pk_bf16_f32 v75, v92, v94
	v_cvt_pk_bf16_f32 v76, v96, v144
	v_cvt_pk_bf16_f32 v77, v145, v87
	v_cvt_pk_bf16_f32 v78, v85, v83
	v_cvt_pk_bf16_f32 v79, v147, v148
	v_cvt_pk_bf16_f32 v80, v89, v90
	v_cvt_pk_bf16_f32 v81, v149, v150
	s_waitcnt lgkmcnt(0)
	v_mfma_f32_32x32x16_bf16 v[18:33], v[66:69], v[222:225], v[18:33]
	v_mfma_f32_32x32x16_bf16 v[18:33], v[70:73], v[226:229], v[18:33]
	v_mfma_f32_32x32x16_bf16 v[18:33], v[74:77], v[230:233], v[18:33]
	v_mfma_f32_32x32x16_bf16 v[18:33], v[78:81], v[234:237], v[18:33]
	v_mfma_f32_32x32x16_bf16 v[2:17], v[66:69], v[238:241], v[2:17]
	v_mfma_f32_32x32x16_bf16 v[2:17], v[70:73], v[242:245], v[2:17]
	v_mfma_f32_32x32x16_bf16 v[2:17], v[74:77], v[246:249], v[2:17]
	v_mfma_f32_32x32x16_bf16 v[2:17], v[78:81], v[250:253], v[2:17]
	v_mov_b32_e32 v142, v151
	s_branch .LBB0_469

; #define LAS __attribute__((address_space(3)))
; __device__ __forceinline__ float pair_max(float v) { float a, b; lohi(v, a, b); return fmaxf(a, b); }
; __device__ __forceinline__ void softmax_pv(f32x16& p0, f32x16& p1, float& m, float& l, f32x16 (&o)[2], LAS float* wsf, const LAS unsigned char* vp, int r32, int hi) {
;     float rm = fmaxf(p0[0], p1[0]);
; #pragma unroll
;     for (int r = 1; r < 16; ++r) rm = fmaxf(rm, fmaxf(p0[r], p1[r]));
;     rm = pair_max(rm);
;     if (__all(rm - m < -151.0f)) return;
;     const float mnew = fmaxf(m, rm), alpha = __builtin_amdgcn_exp2f(m - mnew);
;     m = mnew;
;     float s = 0.f;
; #pragma unroll
;     for (int r = 0; r < 16; ++r) { p0[r] = __builtin_amdgcn_exp2f(p0[r] - mnew); p1[r] = __builtin_amdgcn_exp2f(p1[r] - mnew); s += p0[r] + p1[r]; }
;     l = l * alpha + s;
;     if (__any(alpha != 1.0f)) {
;         if (hi == 0) wsf[r32] = alpha;
; #pragma unroll
;         for (int r = 0; r < 16; ++r) { const float f = wsf[(r & 3) + 8 * (r >> 2) + 4 * hi]; o[0][r] *= f; o[1][r] *= f; }
; template <int VAR>
; __device__ __forceinline__ void attn_unit(LAS unsigned char* lds, const AttnArgs& A, int b, int h, int qb, const int tid) {
;     ...
;                 } else if (VAR == 1) {
;                     const LAS float* eb = EXTL + (576 - tl);
; #pragma unroll
;                     for (int r = 0; r < 16; ++r) { const int c0 = (r & 3) + 8 * (r >> 2); p0[r] += eb[c0]; p1[r] += eb[c0 + 32]; }
;                     softmax_pv(p0, p1, m1, l1, o, wsf, vp, r32, hi);
.LBB0_489:
	s_add_i32 s38, s71, 2
	s_cmp_gt_i32 s38, s11
	s_cselect_b64 s[12:13], -1, 0
	s_cmp_lt_i32 s38, s28
	s_cselect_b64 s[38:39], -1, 0
	s_or_b64 s[12:13], s[12:13], s[38:39]
	s_and_b64 vcc, exec, s[12:13]
	s_cbranch_vccnz .LBB0_496
	s_add_i32 s12, s81, 0xffffe000
	s_and_b32 s50, s12, 0x2000
	v_add_u32_e32 v108, s50, v97
	ds_read_b128 v[126:129], v108
	ds_read_b128 v[130:133], v108 offset:2048
	ds_read_b128 v[134:137], v108 offset:512
	ds_read_b128 v[138:141], v108 offset:2560
	ds_read_b128 v[146:149], v108 offset:4096
	ds_read_b128 v[150:153], v108 offset:4608
	ds_read_b128 v[166:169], v108 offset:6144
	ds_read_b128 v[170:173], v108 offset:6656
	s_waitcnt lgkmcnt(7)
	v_mfma_f32_32x32x16_bf16 v[34:49], v[126:129], v[66:69], 0
	s_waitcnt lgkmcnt(6)
	v_mfma_f32_32x32x16_bf16 v[34:49], v[130:133], v[70:73], v[34:49]
	s_waitcnt lgkmcnt(5)
	v_mfma_f32_32x32x16_bf16 v[50:65], v[134:137], v[66:69], 0
	s_waitcnt lgkmcnt(4)
	v_mfma_f32_32x32x16_bf16 v[50:65], v[138:141], v[70:73], v[50:65]
	s_waitcnt lgkmcnt(3)
	v_mfma_f32_32x32x16_bf16 v[34:49], v[146:149], v[74:77], v[34:49]
	s_waitcnt lgkmcnt(2)
	v_mfma_f32_32x32x16_bf16 v[50:65], v[150:153], v[74:77], v[50:65]
	s_waitcnt lgkmcnt(1)
	v_mfma_f32_32x32x16_bf16 v[34:49], v[166:169], v[78:81], v[34:49]
	s_waitcnt lgkmcnt(0)
	v_mfma_f32_32x32x16_bf16 v[50:65], v[170:173], v[78:81], v[50:65]
	ds_read2_b32 v[206:207], v101 offset1:1
	ds_read2_b32 v[208:209], v101 offset0:32 offset1:33
	ds_read2_b32 v[210:211], v101 offset0:34 offset1:35
	ds_read2_b32 v[212:213], v101 offset0:2 offset1:3
	ds_read2_b32 v[214:215], v101 offset0:8 offset1:9
	ds_read2_b32 v[216:217], v101 offset0:40 offset1:41
	ds_read2_b32 v[218:219], v101 offset0:10 offset1:11
	ds_read2_b32 v[220:221], v101 offset0:42 offset1:43
	ds_read2_b32 v[222:223], v101 offset0:16 offset1:17
	ds_read2_b32 v[224:225], v101 offset0:48 offset1:49
	ds_read2_b32 v[226:227], v101 offset0:18 offset1:19
	ds_read2_b32 v[228:229], v101 offset0:50 offset1:51
	ds_read2_b32 v[230:231], v101 offset0:24 offset1:25
	ds_read2_b32 v[232:233], v101 offset0:56 offset1:57
	ds_read2_b32 v[234:235], v101 offset0:26 offset1:27
	ds_read2_b32 v[236:237], v101 offset0:58 offset1:59
	s_waitcnt lgkmcnt(15)
	v_add_f32_e32 v34, v34, v206
	s_waitcnt lgkmcnt(14)
	v_add_f32_e32 v104, v50, v208
	v_add_f32_e32 v50, v35, v207
	v_add_f32_e32 v35, v51, v209
	s_waitcnt lgkmcnt(13)
	v_add_f32_e32 v52, v52, v210
	s_waitcnt lgkmcnt(12)
	v_add_f32_e32 v51, v36, v212
	v_add_f32_e32 v37, v37, v213
	v_add_f32_e32 v36, v53, v211
	s_waitcnt lgkmcnt(11)
	v_add_f32_e32 v105, v38, v214
	s_waitcnt lgkmcnt(10)
	v_add_f32_e32 v54, v54, v216
	v_add_f32_e32 v53, v39, v215
	v_add_f32_e32 v39, v55, v217
	v_max_f32_e32 v38, v50, v35
	v_max3_f32 v38, v34, v104, v38
	s_waitcnt lgkmcnt(9)
	v_add_f32_e32 v40, v40, v218
	s_waitcnt lgkmcnt(8)
	v_add_f32_e32 v56, v56, v220
	v_add_f32_e32 v55, v41, v219
	v_add_f32_e32 v41, v57, v221
	s_waitcnt lgkmcnt(7)
	v_add_f32_e32 v42, v42, v222
	s_waitcnt lgkmcnt(6)
	v_add_f32_e32 v58, v58, v224
	v_add_f32_e32 v57, v43, v223
	v_add_f32_e32 v43, v59, v225
	s_waitcnt lgkmcnt(5)
	v_add_f32_e32 v59, v44, v226
	s_waitcnt lgkmcnt(4)
	v_add_f32_e32 v60, v60, v228
	v_add_f32_e32 v45, v45, v227
	v_add_f32_e32 v44, v61, v229
	s_waitcnt lgkmcnt(3)
	v_add_f32_e32 v61, v46, v230
	s_waitcnt lgkmcnt(2)
	v_add_f32_e32 v62, v62, v232
	v_add_f32_e32 v47, v47, v231
	v_add_f32_e32 v46, v63, v233
	s_waitcnt lgkmcnt(1)
	v_add_f32_e32 v48, v48, v234
	v_add_f32_e32 v63, v49, v235
	s_waitcnt lgkmcnt(0)
	v_add_u32_e32 v194, s50, v99
	ds_read_b64_tr_b16 v[238:239], v194 offset:16384
	ds_read_b64_tr_b16 v[240:241], v194 offset:16896
	ds_read_b64_tr_b16 v[242:243], v194 offset:17408
	ds_read_b64_tr_b16 v[244:245], v194 offset:17920
	ds_read_b64_tr_b16 v[246:247], v194 offset:18432
	ds_read_b64_tr_b16 v[248:249], v194 offset:18944
	ds_read_b64_tr_b16 v[250:251], v194 offset:19456
	ds_read_b64_tr_b16 v[252:253], v194 offset:19968
	ds_read_b64_tr_b16 v[178:179], v194 offset:20480
	ds_read_b64_tr_b16 v[180:181], v194 offset:20992
	ds_read_b64_tr_b16 v[182:183], v194 offset:21504
	ds_read_b64_tr_b16 v[184:185], v194 offset:22016
	ds_read_b64_tr_b16 v[186:187], v194 offset:22528
	ds_read_b64_tr_b16 v[188:189], v194 offset:23040
	ds_read_b64_tr_b16 v[190:191], v194 offset:23552
	ds_read_b64_tr_b16 v[192:193], v194 offset:24064
	v_add_f32_e32 v49, v65, v237
	v_max_f32_e32 v65, v51, v52
	v_max_f32_e32 v106, v37, v36
	v_max3_f32 v38, v38, v65, v106
	v_max_f32_e32 v65, v105, v54
	v_max_f32_e32 v106, v53, v39
	v_max3_f32 v38, v38, v65, v106
	v_max_f32_e32 v65, v40, v56
	v_max_f32_e32 v106, v55, v41
	v_max3_f32 v38, v38, v65, v106
	v_max_f32_e32 v65, v42, v58
	v_max_f32_e32 v106, v57, v43
	v_max3_f32 v38, v38, v65, v106
	v_max_f32_e32 v65, v59, v60
	v_max_f32_e32 v106, v45, v44
	v_add_f32_e32 v64, v64, v236
	v_max3_f32 v38, v38, v65, v106
	v_max_f32_e32 v65, v61, v62
	v_max_f32_e32 v106, v47, v46
	v_max3_f32 v38, v38, v65, v106
	v_max_f32_e32 v65, v48, v64
	v_max_f32_e32 v106, v63, v49
	v_max3_f32 v38, v38, v65, v106
	v_mov_b32_e32 v65, v38
	s_nop 1
	v_permlane32_swap_b32_e32 v38, v65
	v_max_f32_e32 v65, v65, v65
	v_max_f32_e32 v38, v38, v38
	v_max_f32_e32 v38, v38, v65
	v_sub_f32_e32 v65, v38, v103
	v_cmp_gt_f32_e32 vcc, s36, v65
	s_cmp_eq_u64 vcc, exec
	s_cbranch_scc1 .LBB0_496
	v_max_f32_e32 v38, v38, v38
	v_add_f32_e32 v65, 0x41000000, v103
	v_cmp_gt_f32_e32 vcc, v38, v65
	s_nop 1
	v_cndmask_b32_e32 v38, v103, v38, vcc
	v_sub_f32_e32 v65, v103, v38
	v_exp_f32_e32 v65, v65
	s_nop 0
	v_cmp_neq_f32_e32 vcc, 1.0, v65
	s_cbranch_vccz .LBB0_495
	s_and_saveexec_b64 s[12:13], s[8:9]
	ds_write_b32 v100, v65 offset:36864
	s_or_b64 exec, exec, s[12:13]
	v_add_u32_e32 v103, s68, v0
	ds_read_b128 v[106:109], v103 offset:36960
	ds_read_b128 v[110:113], v103 offset:36928
	ds_read_b128 v[114:117], v103 offset:36896
	ds_read_b128 v[118:121], v103 offset:36864
	s_waitcnt lgkmcnt(3)
	v_pk_mul_f32 v[30:31], v[30:31], v[106:107]
	s_waitcnt lgkmcnt(2)
	v_pk_mul_f32 v[26:27], v[26:27], v[110:111]
	s_waitcnt lgkmcnt(1)
	v_pk_mul_f32 v[22:23], v[22:23], v[114:115]
	s_waitcnt lgkmcnt(0)
	v_pk_mul_f32 v[18:19], v[18:19], v[118:119]
	v_pk_mul_f32 v[14:15], v[14:15], v[106:107]
	v_pk_mul_f32 v[10:11], v[10:11], v[110:111]
	v_pk_mul_f32 v[6:7], v[6:7], v[114:115]
	v_pk_mul_f32 v[32:33], v[32:33], v[108:109]
	v_pk_mul_f32 v[28:29], v[28:29], v[112:113]
	v_pk_mul_f32 v[24:25], v[24:25], v[116:117]
	v_pk_mul_f32 v[20:21], v[20:21], v[120:121]
	v_pk_mul_f32 v[16:17], v[16:17], v[108:109]
	v_pk_mul_f32 v[12:13], v[12:13], v[112:113]
	v_pk_mul_f32 v[8:9], v[8:9], v[116:117]
	v_pk_mul_f32 v[4:5], v[4:5], v[120:121]
	v_pk_mul_f32 v[2:3], v[2:3], v[118:119]
; #define LAS __attribute__((address_space(3)))
; __device__ __forceinline__ unsigned cvtpk(float lo, float hi) { f32x2_t v = {lo, hi}; bf16x2_t b = __builtin_convertvector(v, bf16x2_t); return __builtin_bit_cast(unsigned, b); }
; __device__ __forceinline__ s16x4 vtr(const LAS unsigned char* p) { return __builtin_bit_cast(s16x4, __builtin_amdgcn_ds_read_tr16_b64_v4i16((LAS v4i16_t*)p)); }
; __device__ __forceinline__ void pv(f32x16 (&o)[2], const LAS unsigned char* vp, const f32x16& p0, const f32x16& p1) {
;     u32x4 pw[4];
;     pw[0] = (u32x4){cvtpk(p0[0], p0[1]), cvtpk(p0[2], p0[3]), cvtpk(p0[4], p0[5]), cvtpk(p0[6], p0[7])};
;     pw[1] = (u32x4){cvtpk(p0[8], p0[9]), cvtpk(p0[10], p0[11]), cvtpk(p0[12], p0[13]), cvtpk(p0[14], p0[15])};
;     pw[2] = (u32x4){cvtpk(p1[0], p1[1]), cvtpk(p1[2], p1[3]), cvtpk(p1[4], p1[5]), cvtpk(p1[6], p1[7])};
;     pw[3] = (u32x4){cvtpk(p1[8], p1[9]), cvtpk(p1[10], p1[11]), cvtpk(p1[12], p1[13]), cvtpk(p1[14], p1[15])};
;     __builtin_amdgcn_s_setprio(1);
; #pragma unroll
;     for (int dh = 0; dh < 2; ++dh)
; #pragma unroll
;         for (int ks = 0; ks < 4; ++ks) {
;             const s16x4 lo = vtr(vp + dh * 4096 + ks * 1024), hi_ = vtr(vp + dh * 4096 + ks * 1024 + 512);
;             const bf16x8 vf = __builtin_shufflevector(lo, hi_, 0, 1, 2, 3, 4, 5, 6, 7);
;             o[dh] = __builtin_amdgcn_mfma_f32_32x32x16_bf16(__builtin_bit_cast(bf16x8, pw[ks]), vf, o[dh], 0, 0, 0);
;         }
;     __builtin_amdgcn_s_setprio(0);
; __device__ __forceinline__ void softmax_pv(f32x16& p0, f32x16& p1, float& m, float& l, f32x16 (&o)[2], LAS float* wsf, const LAS unsigned char* vp, int r32, int hi) {
;     ...
;     const float mnew = fmaxf(m, rm), alpha = __builtin_amdgcn_exp2f(m - mnew);
;     m = mnew;
;     float s = 0.f;
; #pragma unroll
;     for (int r = 0; r < 16; ++r) { p0[r] = __builtin_amdgcn_exp2f(p0[r] - mnew); p1[r] = __builtin_amdgcn_exp2f(p1[r] - mnew); s += p0[r] + p1[r]; }
;     l = l * alpha + s;
;     if (__any(alpha != 1.0f)) {
;         if (hi == 0) wsf[r32] = alpha;
; #pragma unroll
;         for (int r = 0; r < 16; ++r) { const float f = wsf[(r & 3) + 8 * (r >> 2) + 4 * hi]; o[0][r] *= f; o[1][r] *= f; }
;     }
;     pv(o, vp, p0, p1);
.LBB0_495:
	v_sub_f32_e32 v34, v34, v38
	v_sub_f32_e32 v103, v104, v38
	v_exp_f32_e32 v34, v34
	v_exp_f32_e32 v103, v103
	v_sub_f32_e32 v50, v50, v38
	v_sub_f32_e32 v35, v35, v38
	v_exp_f32_e32 v50, v50
	v_exp_f32_e32 v104, v35
	v_sub_f32_e32 v51, v51, v38
	v_sub_f32_e32 v52, v52, v38
	v_exp_f32_e32 v51, v51
	v_exp_f32_e32 v52, v52
	v_sub_f32_e32 v37, v37, v38
	v_sub_f32_e32 v36, v36, v38
	v_exp_f32_e32 v37, v37
	v_exp_f32_e32 v107, v36
	v_sub_f32_e32 v105, v105, v38
	v_sub_f32_e32 v54, v54, v38
	v_add_f32_e32 v35, v34, v103
	v_exp_f32_e32 v105, v105
	v_exp_f32_e32 v54, v54
	v_sub_f32_e32 v53, v53, v38
	v_sub_f32_e32 v39, v39, v38
	v_add_f32_e32 v35, 0, v35
	v_add_f32_e32 v106, v50, v104
	v_exp_f32_e32 v53, v53
	v_exp_f32_e32 v39, v39
	v_sub_f32_e32 v40, v40, v38
	v_sub_f32_e32 v56, v56, v38
	v_add_f32_e32 v35, v106, v35
	v_add_f32_e32 v36, v51, v52
	v_exp_f32_e32 v40, v40
	v_exp_f32_e32 v56, v56
	v_sub_f32_e32 v55, v55, v38
	v_sub_f32_e32 v41, v41, v38
	v_add_f32_e32 v35, v36, v35
	v_add_f32_e32 v36, v37, v107
	v_exp_f32_e32 v55, v55
	v_exp_f32_e32 v106, v41
	v_sub_f32_e32 v41, v42, v38
	v_sub_f32_e32 v42, v58, v38
	v_add_f32_e32 v35, v36, v35
	v_add_f32_e32 v36, v105, v54
	v_exp_f32_e32 v41, v41
	v_exp_f32_e32 v58, v42
	v_sub_f32_e32 v42, v57, v38
	v_sub_f32_e32 v43, v43, v38
	v_add_f32_e32 v35, v36, v35
	v_add_f32_e32 v36, v53, v39
	v_exp_f32_e32 v42, v42
	v_exp_f32_e32 v57, v43
	v_sub_f32_e32 v43, v59, v38
	v_sub_f32_e32 v59, v60, v38
	v_add_f32_e32 v35, v36, v35
	v_add_f32_e32 v36, v40, v56
	v_exp_f32_e32 v43, v43
	v_exp_f32_e32 v59, v59
	v_sub_f32_e32 v45, v45, v38
	v_sub_f32_e32 v44, v44, v38
	v_add_f32_e32 v35, v36, v35
	v_add_f32_e32 v36, v55, v106
	v_exp_f32_e32 v45, v45
	v_exp_f32_e32 v60, v44
	v_sub_f32_e32 v44, v61, v38
	v_sub_f32_e32 v61, v62, v38
	v_add_f32_e32 v35, v36, v35
	v_add_f32_e32 v36, v41, v58
	v_exp_f32_e32 v44, v44
	v_exp_f32_e32 v61, v61
	v_sub_f32_e32 v47, v47, v38
	v_sub_f32_e32 v46, v46, v38
	v_add_f32_e32 v35, v36, v35
	v_add_f32_e32 v36, v42, v57
	v_exp_f32_e32 v47, v47
	v_exp_f32_e32 v62, v46
	v_sub_f32_e32 v46, v48, v38
	v_sub_f32_e32 v48, v64, v38
	v_add_f32_e32 v35, v36, v35
	v_add_f32_e32 v36, v43, v59
	v_exp_f32_e32 v46, v46
	v_exp_f32_e32 v64, v48
	v_sub_f32_e32 v48, v63, v38
	v_sub_f32_e32 v49, v49, v38
	v_add_f32_e32 v35, v36, v35
	v_add_f32_e32 v36, v45, v60
	v_exp_f32_e32 v48, v48
	v_exp_f32_e32 v63, v49
	v_add_f32_e32 v35, v36, v35
	v_add_f32_e32 v36, v44, v61
	v_add_f32_e32 v35, v36, v35
	v_add_f32_e32 v36, v47, v62
	v_add_f32_e32 v35, v36, v35
	v_add_f32_e32 v36, v46, v64
	v_add_f32_e32 v35, v36, v35
	v_add_f32_e32 v36, v48, v63
	v_add_f32_e32 v108, v36, v35
	v_fmac_f32_e32 v108, v102, v65
	v_cvt_pk_bf16_f32 v34, v34, v50
	v_cvt_pk_bf16_f32 v35, v51, v37
	v_cvt_pk_bf16_f32 v36, v105, v53
	v_cvt_pk_bf16_f32 v37, v40, v55
	v_cvt_pk_bf16_f32 v40, v41, v42
	v_cvt_pk_bf16_f32 v41, v43, v45
	v_cvt_pk_bf16_f32 v42, v44, v47
	v_cvt_pk_bf16_f32 v43, v46, v48
	v_cvt_pk_bf16_f32 v44, v103, v104
	v_cvt_pk_bf16_f32 v45, v52, v107
	v_cvt_pk_bf16_f32 v46, v54, v39
	v_cvt_pk_bf16_f32 v47, v56, v106
	v_cvt_pk_bf16_f32 v48, v58, v57
	v_cvt_pk_bf16_f32 v49, v59, v60
	v_cvt_pk_bf16_f32 v50, v61, v62
	v_cvt_pk_bf16_f32 v51, v64, v63
	s_waitcnt lgkmcnt(0)
	v_mfma_f32_32x32x16_bf16 v[2:17], v[34:37], v[238:241], v[2:17]
	v_mfma_f32_32x32x16_bf16 v[2:17], v[40:43], v[242:245], v[2:17]
	v_mfma_f32_32x32x16_bf16 v[2:17], v[44:47], v[246:249], v[2:17]
	v_mfma_f32_32x32x16_bf16 v[2:17], v[48:51], v[250:253], v[2:17]
	v_mfma_f32_32x32x16_bf16 v[18:33], v[34:37], v[178:181], v[18:33]
	v_mfma_f32_32x32x16_bf16 v[18:33], v[40:43], v[182:185], v[18:33]
	v_mfma_f32_32x32x16_bf16 v[18:33], v[44:47], v[186:189], v[18:33]
	v_mfma_f32_32x32x16_bf16 v[18:33], v[48:51], v[190:193], v[18:33]
	v_mov_b32_e32 v102, v108
	v_mov_b32_e32 v103, v38

; #define LAS __attribute__((address_space(3)))
; template <int VAR>
; __device__ __forceinline__ void attn_unit(LAS unsigned char* lds, const AttnArgs& A, int b, int h, int qb, const int tid) {
;     ...
;                 for (int d0 = 0; d0 < 4; ++d0) {
;                     const bf16x8 b0 = *(const LAS bf16x8*)(kb + d0 * 2048), b1 = *(const LAS bf16x8*)(kb + d0 * 2048 + 512);
;                     p0 = __builtin_amdgcn_mfma_f32_32x32x16_bf16(b0, qr[d0], p0, 0, 0, 0);
;                     p1 = __builtin_amdgcn_mfma_f32_32x32x16_bf16(b1, qr[d0], p1, 0, 0, 0);
;                 }
;                 __builtin_amdgcn_s_setprio(0);
;                 if (VAR == 0) {
;                     const LAS float* fs = FS + buf * 64 + 4 * hi;
; #pragma unroll
;                     for (int a = 0; a < 4; ++a) {
;                         const f32x4 f0 = *(const LAS f32x4*)(fs + 8 * a), f1 = *(const LAS f32x4*)(fs + 32 + 8 * a);
; #pragma unroll
;                         for (int j = 0; j < 4; ++j) { p0[4 * a + j] += Ft - f0[j]; p1[4 * a + j] += Ft - f1[j]; }
;                     }
;                     if (diag) {
;                         const float tlf = (float)tl;
; #pragma unroll
;                         for (int r = 0; r < 16; ++r) { const float c0 = (float)((r & 3) + 8 * (r >> 2));
;                             p0[r] = __builtin_fmaf(fminf(tlf - c0, 0.f), 1e30f, p0[r]); p1[r] = __builtin_fmaf(fminf(tlf - (c0 + 32.0f), 0.f), 1e30f, p1[r]); }
.LBB0_519:
	s_add_i32 s38, s68, 2
	s_and_b32 s82, s69, 1
	s_cmp_gt_i32 s38, s79
	s_cselect_b64 s[38:39], -1, 0
	s_or_b64 s[38:39], s[38:39], s[70:71]
	s_and_b64 vcc, exec, s[38:39]
	s_cbranch_vccnz .LBB0_528
	s_lshl_b32 s51, s82, 13
	s_lshl_b32 s38, s82, 8
	v_add_u32_e32 v136, s51, v141
	s_add_i32 s50, s38, 0
	s_cmp_lg_u32 s81, s69
	ds_read_b128 v[206:209], v136
	ds_read_b128 v[210:213], v136 offset:2048
	ds_read_b128 v[214:217], v136 offset:512
	ds_read_b128 v[218:221], v136 offset:2560
	ds_read_b128 v[222:225], v136 offset:4096
	ds_read_b128 v[226:229], v136 offset:4608
	ds_read_b128 v[230:233], v136 offset:6144
	ds_read_b128 v[234:237], v136 offset:6656
	v_lshl_add_u32 v147, v142, 2, s50
	ds_read_b128 v[238:241], v147 offset:32768
	ds_read_b128 v[242:245], v147 offset:32800
	ds_read_b128 v[246:249], v147 offset:32896
	ds_read_b128 v[250:253], v147 offset:32928
	ds_read_b128 v[178:181], v147 offset:32832
	ds_read_b128 v[182:185], v147 offset:32960
	ds_read_b128 v[186:189], v147 offset:32864
	ds_read_b128 v[190:193], v147 offset:32992
	s_waitcnt lgkmcnt(15)
	v_mfma_f32_32x32x16_bf16 v[34:49], v[206:209], v[66:69], 0
	s_waitcnt lgkmcnt(14)
	v_mfma_f32_32x32x16_bf16 v[34:49], v[210:213], v[70:73], v[34:49]
	s_waitcnt lgkmcnt(13)
	v_mfma_f32_32x32x16_bf16 v[50:65], v[214:217], v[66:69], 0
	s_waitcnt lgkmcnt(12)
	v_mfma_f32_32x32x16_bf16 v[50:65], v[218:221], v[70:73], v[50:65]
	s_waitcnt lgkmcnt(11)
	v_mfma_f32_32x32x16_bf16 v[34:49], v[222:225], v[74:77], v[34:49]
	s_waitcnt lgkmcnt(10)
	v_mfma_f32_32x32x16_bf16 v[50:65], v[226:229], v[74:77], v[50:65]
	s_waitcnt lgkmcnt(9)
	v_mfma_f32_32x32x16_bf16 v[34:49], v[230:233], v[78:81], v[34:49]
	s_waitcnt lgkmcnt(8)
	v_mfma_f32_32x32x16_bf16 v[50:65], v[234:237], v[78:81], v[50:65]
	s_nop 7
	s_waitcnt lgkmcnt(7)
	v_pk_add_f32 v[136:137], v[98:99], v[238:239] neg_lo:[0,1] neg_hi:[0,1]
	s_nop 1
	v_pk_add_f32 v[136:137], v[34:35], v[136:137]
	s_waitcnt lgkmcnt(5)
	v_pk_add_f32 v[34:35], v[98:99], v[246:247] neg_lo:[0,1] neg_hi:[0,1]
	s_nop 0
	v_pk_add_f32 v[50:51], v[50:51], v[34:35]
	v_pk_add_f32 v[34:35], v[98:99], v[240:241] neg_lo:[0,1] neg_hi:[0,1]
	v_pk_add_f32 v[34:35], v[36:37], v[34:35]
	v_pk_add_f32 v[36:37], v[98:99], v[248:249] neg_lo:[0,1] neg_hi:[0,1]
	s_nop 0
	v_pk_add_f32 v[36:37], v[52:53], v[36:37]
	v_pk_add_f32 v[52:53], v[98:99], v[242:243] neg_lo:[0,1] neg_hi:[0,1]
	s_nop 0
	v_pk_add_f32 v[52:53], v[38:39], v[52:53]
	s_waitcnt lgkmcnt(4)
	v_pk_add_f32 v[38:39], v[98:99], v[250:251] neg_lo:[0,1] neg_hi:[0,1]
	s_nop 0
	v_pk_add_f32 v[54:55], v[54:55], v[38:39]
	v_pk_add_f32 v[38:39], v[98:99], v[244:245] neg_lo:[0,1] neg_hi:[0,1]
	s_nop 0
	v_pk_add_f32 v[38:39], v[40:41], v[38:39]
	v_pk_add_f32 v[40:41], v[98:99], v[252:253] neg_lo:[0,1] neg_hi:[0,1]
	v_pk_add_f32 v[40:41], v[56:57], v[40:41]
	s_waitcnt lgkmcnt(3)
	v_pk_add_f32 v[56:57], v[98:99], v[178:179] neg_lo:[0,1] neg_hi:[0,1]
	s_nop 0
	v_pk_add_f32 v[56:57], v[42:43], v[56:57]
	s_waitcnt lgkmcnt(2)
	v_pk_add_f32 v[42:43], v[98:99], v[182:183] neg_lo:[0,1] neg_hi:[0,1]
	s_nop 0
	v_pk_add_f32 v[58:59], v[58:59], v[42:43]
	v_pk_add_f32 v[42:43], v[98:99], v[180:181] neg_lo:[0,1] neg_hi:[0,1]
	s_nop 0
	v_pk_add_f32 v[42:43], v[44:45], v[42:43]
	v_pk_add_f32 v[44:45], v[98:99], v[184:185] neg_lo:[0,1] neg_hi:[0,1]
	v_pk_add_f32 v[44:45], v[60:61], v[44:45]
	s_waitcnt lgkmcnt(1)
	v_pk_add_f32 v[60:61], v[98:99], v[186:187] neg_lo:[0,1] neg_hi:[0,1]
	s_nop 0
	v_pk_add_f32 v[60:61], v[46:47], v[60:61]
	s_waitcnt lgkmcnt(0)
	v_pk_add_f32 v[46:47], v[98:99], v[190:191] neg_lo:[0,1] neg_hi:[0,1]
	s_nop 0
	v_pk_add_f32 v[62:63], v[62:63], v[46:47]
	v_pk_add_f32 v[46:47], v[98:99], v[188:189] neg_lo:[0,1] neg_hi:[0,1]
	s_nop 0
	v_pk_add_f32 v[46:47], v[48:49], v[46:47]
	v_pk_add_f32 v[48:49], v[98:99], v[192:193] neg_lo:[0,1] neg_hi:[0,1]
	s_nop 0
	v_pk_add_f32 v[48:49], v[64:65], v[48:49]
	v_add_u32_e32 v194, s51, v143
	ds_read_b64_tr_b16 v[206:207], v194 offset:16384
	ds_read_b64_tr_b16 v[208:209], v194 offset:16896
	ds_read_b64_tr_b16 v[210:211], v194 offset:17408
	ds_read_b64_tr_b16 v[212:213], v194 offset:17920
	ds_read_b64_tr_b16 v[214:215], v194 offset:18432
	ds_read_b64_tr_b16 v[216:217], v194 offset:18944
	ds_read_b64_tr_b16 v[218:219], v194 offset:19456
	ds_read_b64_tr_b16 v[220:221], v194 offset:19968
	ds_read_b64_tr_b16 v[222:223], v194 offset:20480
	ds_read_b64_tr_b16 v[224:225], v194 offset:20992
	ds_read_b64_tr_b16 v[226:227], v194 offset:21504
	ds_read_b64_tr_b16 v[228:229], v194 offset:22016
	ds_read_b64_tr_b16 v[230:231], v194 offset:22528
	ds_read_b64_tr_b16 v[232:233], v194 offset:23040
	ds_read_b64_tr_b16 v[234:235], v194 offset:23552
	ds_read_b64_tr_b16 v[236:237], v194 offset:24064
	s_cbranch_scc1 .LBB0_522
	v_pk_fma_f32 v[46:47], v[132:133], s[62:63], v[46:47] op_sel_hi:[1,0,1]
	v_pk_fma_f32 v[60:61], v[128:129], s[62:63], v[60:61] op_sel_hi:[1,0,1]
	v_pk_fma_f32 v[42:43], v[120:121], s[62:63], v[42:43] op_sel_hi:[1,0,1]
	v_pk_fma_f32 v[56:57], v[116:117], s[62:63], v[56:57] op_sel_hi:[1,0,1]
	v_pk_fma_f32 v[38:39], v[112:113], s[62:63], v[38:39] op_sel_hi:[1,0,1]
	v_pk_fma_f32 v[52:53], v[108:109], s[62:63], v[52:53] op_sel_hi:[1,0,1]
	v_pk_fma_f32 v[34:35], v[104:105], s[62:63], v[34:35] op_sel_hi:[1,0,1]
	v_pk_fma_f32 v[136:137], v[100:101], s[62:63], v[136:137] op_sel_hi:[1,0,1]
	v_pk_fma_f32 v[48:49], v[134:135], s[62:63], v[48:49] op_sel_hi:[1,0,1]
	v_pk_fma_f32 v[62:63], v[130:131], s[62:63], v[62:63] op_sel_hi:[1,0,1]
	v_pk_fma_f32 v[44:45], v[126:127], s[62:63], v[44:45] op_sel_hi:[1,0,1]
	v_pk_fma_f32 v[58:59], v[118:119], s[62:63], v[58:59] op_sel_hi:[1,0,1]
	v_pk_fma_f32 v[40:41], v[114:115], s[62:63], v[40:41] op_sel_hi:[1,0,1]
	v_pk_fma_f32 v[54:55], v[110:111], s[62:63], v[54:55] op_sel_hi:[1,0,1]
	v_pk_fma_f32 v[36:37], v[106:107], s[62:63], v[36:37] op_sel_hi:[1,0,1]
	v_pk_fma_f32 v[50:51], v[102:103], s[62:63], v[50:51] op_sel_hi:[1,0,1]

; #define LAS __attribute__((address_space(3)))
; __device__ __forceinline__ unsigned cvtpk(float lo, float hi) { f32x2_t v = {lo, hi}; bf16x2_t b = __builtin_convertvector(v, bf16x2_t); return __builtin_bit_cast(unsigned, b); }
; __device__ __forceinline__ s16x4 vtr(const LAS unsigned char* p) { return __builtin_bit_cast(s16x4, __builtin_amdgcn_ds_read_tr16_b64_v4i16((LAS v4i16_t*)p)); }
; __device__ __forceinline__ void pv(f32x16 (&o)[2], const LAS unsigned char* vp, const f32x16& p0, const f32x16& p1) {
;     u32x4 pw[4];
;     pw[0] = (u32x4){cvtpk(p0[0], p0[1]), cvtpk(p0[2], p0[3]), cvtpk(p0[4], p0[5]), cvtpk(p0[6], p0[7])};
;     pw[1] = (u32x4){cvtpk(p0[8], p0[9]), cvtpk(p0[10], p0[11]), cvtpk(p0[12], p0[13]), cvtpk(p0[14], p0[15])};
;     pw[2] = (u32x4){cvtpk(p1[0], p1[1]), cvtpk(p1[2], p1[3]), cvtpk(p1[4], p1[5]), cvtpk(p1[6], p1[7])};
;     pw[3] = (u32x4){cvtpk(p1[8], p1[9]), cvtpk(p1[10], p1[11]), cvtpk(p1[12], p1[13]), cvtpk(p1[14], p1[15])};
;     __builtin_amdgcn_s_setprio(1);
; #pragma unroll
;     for (int dh = 0; dh < 2; ++dh)
; #pragma unroll
;         for (int ks = 0; ks < 4; ++ks) {
;             const s16x4 lo = vtr(vp + dh * 4096 + ks * 1024), hi_ = vtr(vp + dh * 4096 + ks * 1024 + 512);
;             const bf16x8 vf = __builtin_shufflevector(lo, hi_, 0, 1, 2, 3, 4, 5, 6, 7);
;             o[dh] = __builtin_amdgcn_mfma_f32_32x32x16_bf16(__builtin_bit_cast(bf16x8, pw[ks]), vf, o[dh], 0, 0, 0);
;         }
;     __builtin_amdgcn_s_setprio(0);
; __device__ __forceinline__ void softmax_pv(f32x16& p0, f32x16& p1, float& m, float& l, f32x16 (&o)[2], LAS float* wsf, const LAS unsigned char* vp, int r32, int hi) {
;     ...
;     const float mnew = fmaxf(m, rm), alpha = __builtin_amdgcn_exp2f(m - mnew);
;     m = mnew;
;     float s = 0.f;
; #pragma unroll
;     for (int r = 0; r < 16; ++r) { p0[r] = __builtin_amdgcn_exp2f(p0[r] - mnew); p1[r] = __builtin_amdgcn_exp2f(p1[r] - mnew); s += p0[r] + p1[r]; }
;     l = l * alpha + s;
;     if (__any(alpha != 1.0f)) {
;         if (hi == 0) wsf[r32] = alpha;
; #pragma unroll
;         for (int r = 0; r < 16; ++r) { const float f = wsf[(r & 3) + 8 * (r >> 2) + 4 * hi]; o[0][r] *= f; o[1][r] *= f; }
;     }
;     pv(o, vp, p0, p1);
.LBB0_527:
	v_sub_f32_e32 v136, v136, v64
	v_sub_f32_e32 v50, v50, v64
	v_sub_f32_e32 v34, v34, v64
	v_exp_f32_e32 v136, v136
	v_exp_f32_e32 v50, v50
	v_sub_f32_e32 v137, v137, v64
	v_sub_f32_e32 v51, v51, v64
	v_exp_f32_e32 v148, v34
	v_sub_f32_e32 v34, v36, v64
	v_exp_f32_e32 v137, v137
	v_exp_f32_e32 v51, v51
	v_exp_f32_e32 v149, v34
	v_sub_f32_e32 v34, v35, v64
	v_exp_f32_e32 v35, v34
	v_sub_f32_e32 v34, v37, v64
	v_exp_f32_e32 v150, v34
	v_sub_f32_e32 v37, v52, v64
	v_sub_f32_e32 v52, v54, v64
	v_add_f32_e32 v146, v136, v50
	v_exp_f32_e32 v37, v37
	v_exp_f32_e32 v52, v52
	v_sub_f32_e32 v53, v53, v64
	v_sub_f32_e32 v54, v55, v64
	v_add_f32_e32 v146, 0, v146
	v_add_f32_e32 v147, v137, v51
	v_exp_f32_e32 v53, v53
	v_exp_f32_e32 v54, v54
	v_sub_f32_e32 v38, v38, v64
	v_sub_f32_e32 v40, v40, v64
	v_add_f32_e32 v34, v147, v146
	v_add_f32_e32 v36, v148, v149
	v_exp_f32_e32 v38, v38
	v_exp_f32_e32 v55, v40
	v_sub_f32_e32 v39, v39, v64
	v_sub_f32_e32 v40, v41, v64
	v_add_f32_e32 v34, v36, v34
	v_add_f32_e32 v36, v35, v150
	v_exp_f32_e32 v39, v39
	v_exp_f32_e32 v146, v40
	v_sub_f32_e32 v40, v56, v64
	v_sub_f32_e32 v41, v58, v64
	v_add_f32_e32 v34, v36, v34
	v_add_f32_e32 v36, v37, v52
	v_exp_f32_e32 v40, v40
	v_exp_f32_e32 v56, v41
	v_sub_f32_e32 v41, v57, v64
	v_sub_f32_e32 v57, v59, v64
	v_add_f32_e32 v34, v36, v34
	v_add_f32_e32 v36, v53, v54
	v_exp_f32_e32 v41, v41
	v_exp_f32_e32 v57, v57
	v_sub_f32_e32 v42, v42, v64
	v_sub_f32_e32 v44, v44, v64
	v_add_f32_e32 v34, v36, v34
	v_add_f32_e32 v36, v38, v55
	v_exp_f32_e32 v42, v42
	v_exp_f32_e32 v58, v44
	v_sub_f32_e32 v43, v43, v64
	v_sub_f32_e32 v44, v45, v64
	v_add_f32_e32 v34, v36, v34
	v_add_f32_e32 v36, v39, v146
	v_exp_f32_e32 v43, v43
	v_exp_f32_e32 v59, v44
	v_sub_f32_e32 v44, v60, v64
	v_sub_f32_e32 v45, v62, v64
	v_add_f32_e32 v34, v36, v34
	v_add_f32_e32 v36, v40, v56
	v_exp_f32_e32 v44, v44
	v_exp_f32_e32 v60, v45
	v_sub_f32_e32 v45, v61, v64
	v_sub_f32_e32 v61, v63, v64
	v_add_f32_e32 v34, v36, v34
	v_add_f32_e32 v36, v41, v57
	v_exp_f32_e32 v45, v45
	v_exp_f32_e32 v61, v61
	v_sub_f32_e32 v46, v46, v64
	v_sub_f32_e32 v48, v48, v64
	v_add_f32_e32 v34, v36, v34
	v_add_f32_e32 v36, v42, v58
	v_exp_f32_e32 v46, v46
	v_exp_f32_e32 v62, v48
	v_sub_f32_e32 v47, v47, v64
	v_sub_f32_e32 v48, v49, v64
	v_add_f32_e32 v34, v36, v34
	v_add_f32_e32 v36, v43, v59
	v_exp_f32_e32 v47, v47
	v_exp_f32_e32 v49, v48
	v_add_f32_e32 v34, v36, v34
	v_add_f32_e32 v36, v44, v60
	v_add_f32_e32 v34, v36, v34
	v_add_f32_e32 v36, v45, v61
	v_add_f32_e32 v34, v36, v34
	v_add_f32_e32 v36, v46, v62
	v_add_f32_e32 v34, v36, v34
	v_add_f32_e32 v36, v47, v49
	v_add_f32_e32 v63, v36, v34
	v_fmac_f32_e32 v63, v145, v65
	v_cvt_pk_bf16_f32 v34, v136, v137
	v_cvt_pk_bf16_f32 v35, v148, v35
	v_cvt_pk_bf16_f32 v36, v37, v53
	v_cvt_pk_bf16_f32 v37, v38, v39
	v_cvt_pk_bf16_f32 v38, v40, v41
	v_cvt_pk_bf16_f32 v39, v42, v43
	v_cvt_pk_bf16_f32 v40, v44, v45
	v_cvt_pk_bf16_f32 v41, v46, v47
	v_cvt_pk_bf16_f32 v42, v50, v51
	v_cvt_pk_bf16_f32 v43, v149, v150
	v_cvt_pk_bf16_f32 v44, v52, v54
	v_cvt_pk_bf16_f32 v45, v55, v146
	v_cvt_pk_bf16_f32 v46, v56, v57
	v_cvt_pk_bf16_f32 v47, v58, v59
	v_cvt_pk_bf16_f32 v48, v60, v61
	v_cvt_pk_bf16_f32 v49, v62, v49
	s_waitcnt lgkmcnt(0)
	v_mfma_f32_32x32x16_bf16 v[18:33], v[34:37], v[206:209], v[18:33]
	v_mfma_f32_32x32x16_bf16 v[18:33], v[38:41], v[210:213], v[18:33]
	v_mfma_f32_32x32x16_bf16 v[18:33], v[42:45], v[214:217], v[18:33]
	v_mfma_f32_32x32x16_bf16 v[18:33], v[46:49], v[218:221], v[18:33]
	v_mfma_f32_32x32x16_bf16 v[2:17], v[34:37], v[222:225], v[2:17]
	v_mfma_f32_32x32x16_bf16 v[2:17], v[38:41], v[226:229], v[2:17]
	v_mfma_f32_32x32x16_bf16 v[2:17], v[42:45], v[230:233], v[2:17]
	v_mfma_f32_32x32x16_bf16 v[2:17], v[46:49], v[234:237], v[2:17]
	v_mov_b32_e32 v145, v63
	s_branch .LBB0_534
